# thr indexer MFMAs software-pipelined vs score accumulation; gla_scan loads batched 16 steps per trip
# speedup vs baseline: 1.1215x; 1.0106x over previous
; DI void phase_inproj(const Params& p, char* smem) {
;     ...
;   for (int u = xi; u < 16 * 27 + 16; u += xn) {
;     f32x16 acc[2][2];
;     const int t = (u < 16 * 27) ? (xg * 16 + (u / 27)) * 27 + (u % 27) : n_in + (u - 16 * 27) * 8 + xg;
;     if (t < n_in) {
;       int mt = t / 27, nt = t % 27;
.LBB0_144:
	s_mul_i32 s6, s79, 0x25f
	s_lshr_b32 s6, s6, 16
	s_mul_i32 s7, s6, 0x6c
	s_sub_i32 s7, s79, s7
	s_lshl_b32 s6, s6, 2
	s_and_b32 s10, s7, 3
	s_add_i32 s6, s6, s10
	s_add_i32 s6, s6, s95
	s_lshr_b32 s7, s7, 2
	s_mul_i32 s6, s6, 27
	s_add_i32 s10, s6, s7
	s_cmpk_gt_i32 s10, 0xd7f
	s_mov_b64 s[6:7], -1
	s_cbranch_scc0 .LBB0_142

; #define MFMA(a, b, c) __builtin_amdgcn_mfma_f32_32x32x16_bf16((a), (b), (c), 0, 0, 0)
; DI f32x16 zero16() { f32x16 z; for (int i = 0; i < 16; ++i) z[i] = 0.f; return z; }
; DI void dsa_thr_item(const Params& p, int b, int qblk, char* smem) {
;     ...
;     for (int kt = wave; kt <= qblk; kt += 8) {
;       const bf16x8 k0 = kn0, k1 = kn1;
;       {
;         const int ktn = min(kt + 8, qblk);
;         kn0 = ldg8(kib + (size_t)ktn * 1024); kn1 = ldg8(kib + (size_t)ktn * 1024 + 512);
;       }
;       float sc[16];
;       {
;         f32x16 a = zero16();
;         a = MFMA(k0, *reinterpret_cast<const bf16x8*>(qil + 256), a);
;         a = MFMA(k1, *reinterpret_cast<const bf16x8*>(qil + 256 + 16), a);
; #pragma unroll
;         for (int i = 0; i < 16; ++i) sc[i] = a[i];
;       }
; #pragma unroll
;       for (int hd = 0; hd < 8; ++hd) {
;         f32x16 a = zero16();
;         a = MFMA(k0, *reinterpret_cast<const bf16x8*>(qil + hd * 32), a);
;         a = MFMA(k1, *reinterpret_cast<const bf16x8*>(qil + hd * 32 + 16), a);
;         const float wh = wq[hd];
; #pragma unroll
;         for (int i = 0; i < 16; ++i) sc[i] = fmaf(fabsf(a[i]), wh, sc[i]);
;       }
.LBB0_268:
	v_mov_b32_e32 v97, v96
	v_add_u32_e32 v96, 8, v97
	v_min_i32_e32 v52, s71, v96
	v_lshlrev_b64 v[0:1], 11, v[52:53]
	s_waitcnt vmcnt(0)
	v_mov_b64_e32 v[42:43], v[38:39]
	s_waitcnt vmcnt(0)
	v_mov_b64_e32 v[46:47], v[34:35]
	v_lshl_add_u64 v[0:1], v[54:55], 0, v[0:1]
	v_mov_b64_e32 v[40:41], v[36:37]
	v_mov_b64_e32 v[44:45], v[32:33]
	global_load_dwordx4 v[32:35], v[0:1], off
	global_load_dwordx4 v[36:39], v[0:1], off offset:1024
	ds_read_b128 v[0:3], v216 offset:33792
	ds_read_b128 v[4:7], v216 offset:33824
	ds_read_b128 v[8:11], v216 offset:33280
	ds_read_b128 v[12:15], v216 offset:33312
	s_waitcnt lgkmcnt(2)
	v_mfma_f32_32x32x16_bf16 v[104:119], v[44:47], v[0:3], 0
	v_mfma_f32_32x32x16_bf16 v[104:119], v[40:43], v[4:7], v[104:119]
	v_cmp_ne_u32_e64 s[0:1], s71, v97
	s_mov_b64 s[62:63], 0
	s_waitcnt lgkmcnt(0)
	v_mfma_f32_32x32x16_bf16 v[120:135], v[44:47], v[8:11], 0
	v_mfma_f32_32x32x16_bf16 v[120:135], v[40:43], v[12:15], v[120:135]
	ds_read_b128 v[0:3], v216 offset:33344
	ds_read_b128 v[4:7], v216 offset:33376
	s_waitcnt lgkmcnt(0)
	v_mfma_f32_32x32x16_bf16 v[136:151], v[44:47], v[0:3], 0
	v_mfma_f32_32x32x16_bf16 v[136:151], v[40:43], v[4:7], v[136:151]
	ds_read_b128 v[8:11], v216 offset:33408
	ds_read_b128 v[12:15], v216 offset:33440
	s_nop 4
	v_fma_f32 v152, |v120|, v79, v104
	v_fma_f32 v153, |v121|, v79, v105
	v_fma_f32 v154, |v122|, v79, v106
	v_fma_f32 v155, |v123|, v79, v107
	v_fma_f32 v156, |v124|, v79, v108
	v_fma_f32 v157, |v125|, v79, v109
	v_fma_f32 v158, |v126|, v79, v110
	v_fma_f32 v159, |v127|, v79, v111
	v_fma_f32 v160, |v128|, v79, v112
	v_fma_f32 v161, |v129|, v79, v113
	v_fma_f32 v98, |v130|, v79, v114
	v_fma_f32 v99, |v131|, v79, v115
	v_fma_f32 v100, |v132|, v79, v116
	v_fma_f32 v101, |v133|, v79, v117
	v_fma_f32 v102, |v134|, v79, v118
	v_fma_f32 v103, |v135|, v79, v119
	s_waitcnt lgkmcnt(0)
	v_mfma_f32_32x32x16_bf16 v[104:119], v[44:47], v[8:11], 0
	v_mfma_f32_32x32x16_bf16 v[104:119], v[40:43], v[12:15], v[104:119]
	ds_read_b128 v[0:3], v216 offset:33472
	ds_read_b128 v[4:7], v216 offset:33504
	v_fma_f32 v152, |v136|, v80, v152
	v_fma_f32 v153, |v137|, v80, v153
	v_fma_f32 v154, |v138|, v80, v154
	v_fma_f32 v155, |v139|, v80, v155
	v_fma_f32 v156, |v140|, v80, v156
	v_fma_f32 v157, |v141|, v80, v157
	v_fma_f32 v158, |v142|, v80, v158
	v_fma_f32 v159, |v143|, v80, v159
	v_fma_f32 v160, |v144|, v80, v160
	v_fma_f32 v161, |v145|, v80, v161
	v_fma_f32 v98, |v146|, v80, v98
	v_fma_f32 v99, |v147|, v80, v99
	v_fma_f32 v100, |v148|, v80, v100
	v_fma_f32 v101, |v149|, v80, v101
	v_fma_f32 v102, |v150|, v80, v102
	v_fma_f32 v103, |v151|, v80, v103
	s_waitcnt lgkmcnt(0)
	v_mfma_f32_32x32x16_bf16 v[120:135], v[44:47], v[0:3], 0
	v_mfma_f32_32x32x16_bf16 v[120:135], v[40:43], v[4:7], v[120:135]
	ds_read_b128 v[8:11], v216 offset:33536
	ds_read_b128 v[12:15], v216 offset:33568
	v_fma_f32 v152, |v104|, v81, v152
	v_fma_f32 v153, |v105|, v81, v153
	v_fma_f32 v154, |v106|, v81, v154
	v_fma_f32 v155, |v107|, v81, v155
	v_fma_f32 v156, |v108|, v81, v156
	v_fma_f32 v157, |v109|, v81, v157
	v_fma_f32 v158, |v110|, v81, v158
	v_fma_f32 v159, |v111|, v81, v159
	v_fma_f32 v160, |v112|, v81, v160
	v_fma_f32 v161, |v113|, v81, v161
	v_fma_f32 v98, |v114|, v81, v98
	v_fma_f32 v99, |v115|, v81, v99
	v_fma_f32 v100, |v116|, v81, v100
	v_fma_f32 v101, |v117|, v81, v101
	v_fma_f32 v102, |v118|, v81, v102
	v_fma_f32 v103, |v119|, v81, v103
	s_waitcnt lgkmcnt(0)
; #define MFMA(a, b, c) __builtin_amdgcn_mfma_f32_32x32x16_bf16((a), (b), (c), 0, 0, 0)
; DI int crow(int i, int h) { return (i & 3) + 8 * (i >> 2) + 4 * h; }
; DI f32x16 zero16() { f32x16 z; for (int i = 0; i < 16; ++i) z[i] = 0.f; return z; }
; DI void dsa_thr_item(const Params& p, int b, int qblk, char* smem) {
;     ...
; #pragma unroll
;       for (int hd = 0; hd < 8; ++hd) {
;         f32x16 a = zero16();
;         a = MFMA(k0, *reinterpret_cast<const bf16x8*>(qil + hd * 32), a);
;         a = MFMA(k1, *reinterpret_cast<const bf16x8*>(qil + hd * 32 + 16), a);
;         const float wh = wq[hd];
; #pragma unroll
;         for (int i = 0; i < 16; ++i) sc[i] = fmaf(fabsf(a[i]), wh, sc[i]);
;       }
;       if (kt == qblk) {
; #pragma unroll
;         for (int i = 0; i < 16; ++i) {
;           int kp = kt * 32 + crow(i, lh);
;           unsigned ky = fkey(sc[i]);
;           unsigned hi = (ky >> shift);
;           if (kp <= q0 + lr && (hi >> 8) == mypref) atomicAdd(&hist[(hi & 255u) * 32 + lr], 1u);
;         }
;       } else {
; #pragma unroll
;         for (int i = 0; i < 16; ++i) {
;           unsigned ky = fkey(sc[i]);
;           unsigned hi = (ky >> shift);
;           if ((hi >> 8) == mypref) atomicAdd(&hist[(hi & 255u) * 32 + lr], 1u);
	v_mfma_f32_32x32x16_bf16 v[136:151], v[44:47], v[8:11], 0
	v_mfma_f32_32x32x16_bf16 v[136:151], v[40:43], v[12:15], v[136:151]
	ds_read_b128 v[0:3], v216 offset:33600
	ds_read_b128 v[4:7], v216 offset:33632
	v_fma_f32 v152, |v120|, v82, v152
	v_fma_f32 v153, |v121|, v82, v153
	v_fma_f32 v154, |v122|, v82, v154
	v_fma_f32 v155, |v123|, v82, v155
	v_fma_f32 v156, |v124|, v82, v156
	v_fma_f32 v157, |v125|, v82, v157
	v_fma_f32 v158, |v126|, v82, v158
	v_fma_f32 v159, |v127|, v82, v159
	v_fma_f32 v160, |v128|, v82, v160
	v_fma_f32 v161, |v129|, v82, v161
	v_fma_f32 v98, |v130|, v82, v98
	v_fma_f32 v99, |v131|, v82, v99
	v_fma_f32 v100, |v132|, v82, v100
	v_fma_f32 v101, |v133|, v82, v101
	v_fma_f32 v102, |v134|, v82, v102
	v_fma_f32 v103, |v135|, v82, v103
	s_waitcnt lgkmcnt(0)
	v_mfma_f32_32x32x16_bf16 v[104:119], v[44:47], v[0:3], 0
	v_mfma_f32_32x32x16_bf16 v[104:119], v[40:43], v[4:7], v[104:119]
	ds_read_b128 v[8:11], v216 offset:33664
	ds_read_b128 v[12:15], v216 offset:33696
	v_fma_f32 v152, |v136|, v83, v152
	v_fma_f32 v153, |v137|, v83, v153
	v_fma_f32 v154, |v138|, v83, v154
	v_fma_f32 v155, |v139|, v83, v155
	v_fma_f32 v156, |v140|, v83, v156
	v_fma_f32 v157, |v141|, v83, v157
	v_fma_f32 v158, |v142|, v83, v158
	v_fma_f32 v159, |v143|, v83, v159
	v_fma_f32 v160, |v144|, v83, v160
	v_fma_f32 v161, |v145|, v83, v161
	v_fma_f32 v98, |v146|, v83, v98
	v_fma_f32 v99, |v147|, v83, v99
	v_fma_f32 v100, |v148|, v83, v100
	v_fma_f32 v101, |v149|, v83, v101
	v_fma_f32 v102, |v150|, v83, v102
	v_fma_f32 v103, |v151|, v83, v103
	s_waitcnt lgkmcnt(0)
	v_mfma_f32_32x32x16_bf16 v[120:135], v[44:47], v[8:11], 0
	v_mfma_f32_32x32x16_bf16 v[120:135], v[40:43], v[12:15], v[120:135]
	ds_read_b128 v[0:3], v216 offset:33728
	ds_read_b128 v[4:7], v216 offset:33760
	v_fma_f32 v152, |v104|, v84, v152
	v_fma_f32 v153, |v105|, v84, v153
	v_fma_f32 v154, |v106|, v84, v154
	v_fma_f32 v155, |v107|, v84, v155
	v_fma_f32 v156, |v108|, v84, v156
	v_fma_f32 v157, |v109|, v84, v157
	v_fma_f32 v158, |v110|, v84, v158
	v_fma_f32 v159, |v111|, v84, v159
	v_fma_f32 v160, |v112|, v84, v160
	v_fma_f32 v161, |v113|, v84, v161
	v_fma_f32 v98, |v114|, v84, v98
	v_fma_f32 v99, |v115|, v84, v99
	v_fma_f32 v100, |v116|, v84, v100
	v_fma_f32 v101, |v117|, v84, v101
	v_fma_f32 v102, |v118|, v84, v102
	v_fma_f32 v103, |v119|, v84, v103
	s_waitcnt lgkmcnt(0)
	v_mfma_f32_32x32x16_bf16 v[136:151], v[44:47], v[0:3], 0
	v_mfma_f32_32x32x16_bf16 v[136:151], v[40:43], v[4:7], v[136:151]
	v_fma_f32 v152, |v120|, v85, v152
	v_fma_f32 v153, |v121|, v85, v153
	v_fma_f32 v154, |v122|, v85, v154
	v_fma_f32 v155, |v123|, v85, v155
	v_fma_f32 v156, |v124|, v85, v156
	v_fma_f32 v157, |v125|, v85, v157
	v_fma_f32 v158, |v126|, v85, v158
	v_fma_f32 v159, |v127|, v85, v159
	v_fma_f32 v160, |v128|, v85, v160
	v_fma_f32 v161, |v129|, v85, v161
	v_fma_f32 v98, |v130|, v85, v98
	v_fma_f32 v99, |v131|, v85, v99
	v_fma_f32 v100, |v132|, v85, v100
	v_fma_f32 v101, |v133|, v85, v101
	v_fma_f32 v102, |v134|, v85, v102
	v_fma_f32 v103, |v135|, v85, v103
	v_fma_f32 v40, |v136|, v86, v152
	v_fma_f32 v22, |v137|, v86, v153
	v_fma_f32 v21, |v138|, v86, v154
	v_fma_f32 v20, |v139|, v86, v155
	v_fma_f32 v19, |v140|, v86, v156
	v_fma_f32 v18, |v141|, v86, v157
	v_fma_f32 v17, |v142|, v86, v158
	v_fma_f32 v16, |v143|, v86, v159
	v_fma_f32 v7, |v144|, v86, v160
	v_fma_f32 v6, |v145|, v86, v161
	v_fma_f32 v5, |v146|, v86, v98
	v_fma_f32 v4, |v147|, v86, v99
	v_fma_f32 v3, |v148|, v86, v100
	v_fma_f32 v2, |v149|, v86, v101
	v_fma_f32 v1, |v150|, v86, v102
	v_fma_f32 v0, |v151|, v86, v103
	v_ashrrev_i32_e32 v8, 31, v40
	v_bitop3_b32 v8, v8, v40, s67 bitop3:0x36
	v_lshrrev_b32_e32 v9, s58, v8
	v_lshrrev_b32_e32 v8, 8, v9
	v_cmp_eq_u32_e64 s[52:53], v8, v94
	s_and_saveexec_b64 s[64:65], s[0:1]
	s_xor_b64 s[64:65], exec, s[64:65]
	s_cbranch_execnz .LBB0_271
	s_andn2_saveexec_b64 s[64:65], s[64:65]
	s_cbranch_execnz .LBB0_302

; DI void gla_scan(const Params& p) {
;     ...
;   for (int u = gtid; u < 32 * 2048; u += gn) {
;     const int bh = u >> 11, rem = u & 2047, e = rem >> 4, d4 = (rem & 15) * 4;
;     f32x4 st = {0.f, 0.f, 0.f, 0.f};
; #pragma unroll 4
;     for (int n = 0; n < 64; ++n) {
;       const int item = bh * 64 + n;
;       st4bf(prev + ((size_t)item * 128 + e) * 64 + d4, st[0], st[1], st[2], st[3]);
;       f32x4 dc = *reinterpret_cast<const f32x4*>(decay + item * 64 + d4);
;       f32x4 kv = *reinterpret_cast<const f32x4*>(kvT + ((size_t)item * 128 + e) * 64 + d4);
;       st = dc * st + kv;
;     }
;   }
.LBB0_451:
	v_add_u32_e32 v12, s5, v0
	v_add_u32_e32 v13, s16, v2
	v_add_u32_e32 v14, s4, v4
	global_load_dwordx4 v[32:35], v12, s[96:97]
	global_load_dwordx4 v[36:39], v13, s[96:97]
	v_add_u32_e32 v13, 0x8000, v13
	global_load_dwordx4 v[40:43], v12, s[96:97] offset:256
	global_load_dwordx4 v[44:47], v13, s[96:97]
	v_add_u32_e32 v13, 0x8000, v13
	global_load_dwordx4 v[48:51], v12, s[96:97] offset:512
	global_load_dwordx4 v[52:55], v13, s[96:97]
	v_add_u32_e32 v13, 0x8000, v13
	global_load_dwordx4 v[56:59], v12, s[96:97] offset:768
	global_load_dwordx4 v[60:63], v13, s[96:97]
	v_add_u32_e32 v13, 0x8000, v13
	global_load_dwordx4 v[64:67], v12, s[96:97] offset:1024
	global_load_dwordx4 v[68:71], v13, s[96:97]
	v_add_u32_e32 v13, 0x8000, v13
	global_load_dwordx4 v[72:75], v12, s[96:97] offset:1280
	global_load_dwordx4 v[76:79], v13, s[96:97]
	v_add_u32_e32 v13, 0x8000, v13
	global_load_dwordx4 v[80:83], v12, s[96:97] offset:1536
	global_load_dwordx4 v[84:87], v13, s[96:97]
	v_add_u32_e32 v13, 0x8000, v13
	global_load_dwordx4 v[88:91], v12, s[96:97] offset:1792
	global_load_dwordx4 v[92:95], v13, s[96:97]
	v_add_u32_e32 v13, 0x8000, v13
	global_load_dwordx4 v[96:99], v12, s[96:97] offset:2048
	global_load_dwordx4 v[100:103], v13, s[96:97]
	v_add_u32_e32 v13, 0x8000, v13
	global_load_dwordx4 v[104:107], v12, s[96:97] offset:2304
	global_load_dwordx4 v[108:111], v13, s[96:97]
	v_add_u32_e32 v13, 0x8000, v13
	global_load_dwordx4 v[112:115], v12, s[96:97] offset:2560
	global_load_dwordx4 v[116:119], v13, s[96:97]
	v_add_u32_e32 v13, 0x8000, v13
	global_load_dwordx4 v[120:123], v12, s[96:97] offset:2816
	global_load_dwordx4 v[124:127], v13, s[96:97]
	v_add_u32_e32 v13, 0x8000, v13
	global_load_dwordx4 v[128:131], v12, s[96:97] offset:3072
	global_load_dwordx4 v[132:135], v13, s[96:97]
	v_add_u32_e32 v13, 0x8000, v13
	global_load_dwordx4 v[144:147], v12, s[96:97] offset:3328
	global_load_dwordx4 v[148:151], v13, s[96:97]
	v_add_u32_e32 v13, 0x8000, v13
	global_load_dwordx4 v[152:155], v12, s[96:97] offset:3584
	global_load_dwordx4 v[156:159], v13, s[96:97]
	v_add_u32_e32 v13, 0x8000, v13
	global_load_dwordx4 v[184:187], v12, s[96:97] offset:3840
	global_load_dwordx4 v[188:191], v13, s[96:97]
	v_add_u32_e32 v13, 0x8000, v13
	v_cvt_pk_bf16_f32 v16, v6, v7
	v_cvt_pk_bf16_f32 v17, v8, v9
	global_store_dwordx2 v14, v[16:17], s[96:97]
	v_add_u32_e32 v14, 0x4000, v14
	s_waitcnt vmcnt(31)
	v_pk_fma_f32 v[6:7], v[6:7], v[32:33], v[36:37]
	v_pk_fma_f32 v[8:9], v[8:9], v[34:35], v[38:39]
	v_cvt_pk_bf16_f32 v16, v6, v7
	v_cvt_pk_bf16_f32 v17, v8, v9
	global_store_dwordx2 v14, v[16:17], s[96:97]
	v_add_u32_e32 v14, 0x4000, v14
	s_waitcnt vmcnt(30)
	v_pk_fma_f32 v[6:7], v[6:7], v[40:41], v[44:45]
	v_pk_fma_f32 v[8:9], v[8:9], v[42:43], v[46:47]
	v_cvt_pk_bf16_f32 v16, v6, v7
	v_cvt_pk_bf16_f32 v17, v8, v9
	global_store_dwordx2 v14, v[16:17], s[96:97]
	v_add_u32_e32 v14, 0x4000, v14
	s_waitcnt vmcnt(29)
	v_pk_fma_f32 v[6:7], v[6:7], v[48:49], v[52:53]
	v_pk_fma_f32 v[8:9], v[8:9], v[50:51], v[54:55]
	v_cvt_pk_bf16_f32 v16, v6, v7
	v_cvt_pk_bf16_f32 v17, v8, v9
	global_store_dwordx2 v14, v[16:17], s[96:97]
	v_add_u32_e32 v14, 0x4000, v14
	s_waitcnt vmcnt(28)
	v_pk_fma_f32 v[6:7], v[6:7], v[56:57], v[60:61]
	v_pk_fma_f32 v[8:9], v[8:9], v[58:59], v[62:63]
	v_cvt_pk_bf16_f32 v16, v6, v7
	v_cvt_pk_bf16_f32 v17, v8, v9
	global_store_dwordx2 v14, v[16:17], s[96:97]
	v_add_u32_e32 v14, 0x4000, v14
	s_waitcnt vmcnt(27)
	v_pk_fma_f32 v[6:7], v[6:7], v[64:65], v[68:69]
	v_pk_fma_f32 v[8:9], v[8:9], v[66:67], v[70:71]
	v_cvt_pk_bf16_f32 v16, v6, v7
	v_cvt_pk_bf16_f32 v17, v8, v9
	global_store_dwordx2 v14, v[16:17], s[96:97]
	v_add_u32_e32 v14, 0x4000, v14
	s_waitcnt vmcnt(26)
	v_pk_fma_f32 v[6:7], v[6:7], v[72:73], v[76:77]
	v_pk_fma_f32 v[8:9], v[8:9], v[74:75], v[78:79]
	v_cvt_pk_bf16_f32 v16, v6, v7
	v_cvt_pk_bf16_f32 v17, v8, v9
	global_store_dwordx2 v14, v[16:17], s[96:97]
	v_add_u32_e32 v14, 0x4000, v14
	s_waitcnt vmcnt(25)
	v_pk_fma_f32 v[6:7], v[6:7], v[80:81], v[84:85]
	v_pk_fma_f32 v[8:9], v[8:9], v[82:83], v[86:87]
	v_cvt_pk_bf16_f32 v16, v6, v7
	v_cvt_pk_bf16_f32 v17, v8, v9
	global_store_dwordx2 v14, v[16:17], s[96:97]
	v_add_u32_e32 v14, 0x4000, v14
	s_waitcnt vmcnt(24)
	v_pk_fma_f32 v[6:7], v[6:7], v[88:89], v[92:93]
	v_pk_fma_f32 v[8:9], v[8:9], v[90:91], v[94:95]
	v_cvt_pk_bf16_f32 v16, v6, v7
	v_cvt_pk_bf16_f32 v17, v8, v9
	global_store_dwordx2 v14, v[16:17], s[96:97]
	v_add_u32_e32 v14, 0x4000, v14
	s_waitcnt vmcnt(23)
	v_pk_fma_f32 v[6:7], v[6:7], v[96:97], v[100:101]
	v_pk_fma_f32 v[8:9], v[8:9], v[98:99], v[102:103]
	v_cvt_pk_bf16_f32 v16, v6, v7
	v_cvt_pk_bf16_f32 v17, v8, v9
	global_store_dwordx2 v14, v[16:17], s[96:97]
	v_add_u32_e32 v14, 0x4000, v14
	s_waitcnt vmcnt(22)
	v_pk_fma_f32 v[6:7], v[6:7], v[104:105], v[108:109]
	v_pk_fma_f32 v[8:9], v[8:9], v[106:107], v[110:111]
	v_cvt_pk_bf16_f32 v16, v6, v7
	v_cvt_pk_bf16_f32 v17, v8, v9
	global_store_dwordx2 v14, v[16:17], s[96:97]
	v_add_u32_e32 v14, 0x4000, v14
	s_waitcnt vmcnt(21)
	v_pk_fma_f32 v[6:7], v[6:7], v[112:113], v[116:117]
	v_pk_fma_f32 v[8:9], v[8:9], v[114:115], v[118:119]
	v_cvt_pk_bf16_f32 v16, v6, v7
	v_cvt_pk_bf16_f32 v17, v8, v9
	global_store_dwordx2 v14, v[16:17], s[96:97]
	v_add_u32_e32 v14, 0x4000, v14
	s_waitcnt vmcnt(20)
	v_pk_fma_f32 v[6:7], v[6:7], v[120:121], v[124:125]
	v_pk_fma_f32 v[8:9], v[8:9], v[122:123], v[126:127]
	v_cvt_pk_bf16_f32 v16, v6, v7
	v_cvt_pk_bf16_f32 v17, v8, v9
	global_store_dwordx2 v14, v[16:17], s[96:97]
	v_add_u32_e32 v14, 0x4000, v14
	s_waitcnt vmcnt(19)
	v_pk_fma_f32 v[6:7], v[6:7], v[128:129], v[132:133]
	v_pk_fma_f32 v[8:9], v[8:9], v[130:131], v[134:135]
	v_cvt_pk_bf16_f32 v16, v6, v7
	v_cvt_pk_bf16_f32 v17, v8, v9
	global_store_dwordx2 v14, v[16:17], s[96:97]
	v_add_u32_e32 v14, 0x4000, v14
	s_waitcnt vmcnt(18)
	v_pk_fma_f32 v[6:7], v[6:7], v[144:145], v[148:149]
	v_pk_fma_f32 v[8:9], v[8:9], v[146:147], v[150:151]
	v_cvt_pk_bf16_f32 v16, v6, v7
	v_cvt_pk_bf16_f32 v17, v8, v9
	global_store_dwordx2 v14, v[16:17], s[96:97]
	v_add_u32_e32 v14, 0x4000, v14
	s_waitcnt vmcnt(17)
	v_pk_fma_f32 v[6:7], v[6:7], v[152:153], v[156:157]
	v_pk_fma_f32 v[8:9], v[8:9], v[154:155], v[158:159]
	v_cvt_pk_bf16_f32 v16, v6, v7
	v_cvt_pk_bf16_f32 v17, v8, v9
	global_store_dwordx2 v14, v[16:17], s[96:97]
	v_add_u32_e32 v14, 0x4000, v14
	s_waitcnt vmcnt(16)
	v_pk_fma_f32 v[6:7], v[6:7], v[184:185], v[188:189]
	v_pk_fma_f32 v[8:9], v[8:9], v[186:187], v[190:191]
	v_add_u32_e32 v0, 0x1000, v0
	v_add_u32_e32 v2, 0x80000, v2
	v_add_u32_e32 v4, 0x40000, v4
	s_add_i32 s24, s24, -16
	s_cmp_eq_u32 s24, 0
	s_cbranch_scc0 .LBB0_451
	v_readlane_b32 s24, v255, 5
	v_add_u32_e32 v10, s3, v10
	v_readlane_b32 s25, v255, 6
	v_add_u32_e32 v11, s24, v11
	v_cmp_lt_i32_e32 vcc, s23, v11
	s_or_b64 s[6:7], vcc, s[6:7]
	s_andn2_b64 exec, exec, s[6:7]
	s_cbranch_execnz .LBB0_450

; #define WAIT_V(n) asm volatile("s_waitcnt vmcnt(%0)" ::"n"(n) : "memory")
; #define RAW_BARRIER() do { asm volatile("s_waitcnt lgkmcnt(0)" ::: "memory"); __builtin_amdgcn_s_barrier(); asm volatile("" ::: "memory"); } while (0)
; #define GLDS_STAGE(slot, kt) do { _Pragma("unroll") for (int i = 0; i < 6; ++i) \
;     __builtin_amdgcn_global_load_lds((const unsigned*)(src[i] + (kt) * 64), (__attribute__((address_space(3))) unsigned*)(smem + (slot) * G_STAGE + (wave + 8 * i) * 1024), 16, 0, 0); } while (0)
; DI void gemm_tile(const u16* __restrict__ X, int ldx, const u16* __restrict__ Wt, int ldw, int K, char* smem,
;                   f32x16 (&acc)[2][2]) {
;     ...
;   const int nk = K / 64;
;   const u16* src[6];
; #pragma unroll
;   for (int i = 0; i < 6; ++i) {
;     const int R = 8 * (wave + 8 * i) + (lane >> 3);
;     const int c = (lane & 7) ^ ((R >> 1) & 7);
;     src[i] = (i < 4) ? (X + (size_t)R * ldx + c * 8) : (Wt + (size_t)(R - 256) * ldw + c * 8);
;   }
;     ...
;   int offA[2], offB[2], xa[2], xb[2];
; #pragma unroll
;   for (int ft = 0; ft < 2; ++ft) { const int R = 256 + fw * 64 + ft * 32 + lr; offA[ft] = R * 128; xa[ft] = (R >> 1) & 7; }
; #pragma unroll
;   for (int tt = 0; tt < 2; ++tt) { const int R = tq * 64 + tt * 32 + lr; offB[tt] = R * 128; xb[tt] = (R >> 1) & 7; }
;   GLDS_STAGE(0, 0); GLDS_STAGE(1, 1); WAIT_V(6); RAW_BARRIER();
;   int cur = 0;
;   for (int kt = 0; kt < nk; ++kt) {
;     const int nxt = (cur >= 1) ? cur - 1 : 2;
;     if (kt + 2 < nk) GLDS_STAGE(nxt, kt + 2);
; template <int MODE>
; DI void phase_gemm(const Params& p, const u16* X, const u16* Wt, int N, const float* resid, float* outf, u16* outb, int ldo, char* smem) {
;     ...
;   for (int u = xi; u < per_group; u += xn) {
;     const int mt = xg + 8 * (u / ntn), nt = u % ntn;
;     f32x16 acc[2][2];
;     gemm_tile(X + (size_t)mt * 256 * 1024, 1024, Wt + (size_t)nt * 128 * 1024, 1024, 1024, smem, acc);
.LBB0_906:
	s_lshr_b32 s98, s3, 6
	s_lshl_b32 s98, s98, 6
	s_and_b32 s99, s3, 3
	s_lshl_b32 s99, s99, 4
	s_add_i32 s98, s98, s99
	s_bfe_u32 s99, s3, 0x40002
	s_add_i32 s98, s98, s99
	s_lshl_b32 s99, s98, 17
	s_lshr_b32 s0, s98, 1
	s_and_b32 s0, s0, 0x78
	s_or_b32 s76, s0, s33
	s_and_b32 s6, s99, 0x1e0000
	s_lshl_b32 s0, s76, 19
	v_lshl_add_u64 v[0:1], v[106:107], 0, s[0:1]
	s_lshl_b32 s0, s6, 1
	v_readfirstlane_b32 s6, v143
	v_lshl_add_u64 v[64:65], v[0:1], 0, v[122:123]
	s_mov_b32 m0, s6
	v_readfirstlane_b32 s85, v131
	v_lshl_add_u64 v[0:1], v[64:65], 0, s[8:9]
	s_mov_b64 s[4:5], 0x40000
	global_load_lds_dwordx4 v[64:65], off
	s_mov_b32 m0, s85
	v_readfirstlane_b32 s84, v132
	v_lshl_add_u64 v[2:3], v[64:65], 0, s[4:5]
	s_mov_b64 s[4:5], 0x60000
	global_load_lds_dwordx4 v[0:1], off
	s_mov_b32 m0, s84
	v_readfirstlane_b32 s81, v133
	v_lshl_add_u64 v[4:5], v[64:65], 0, s[4:5]
	v_lshl_add_u64 v[6:7], v[108:109], 0, s[0:1]
	global_load_lds_dwordx4 v[2:3], off
	s_mov_b32 m0, s81
	v_readfirstlane_b32 s80, v134
	v_lshl_add_u64 v[66:67], v[6:7], 0, v[122:123]
	global_load_lds_dwordx4 v[4:5], off
	s_mov_b32 m0, s80
	v_readfirstlane_b32 s79, v135
	v_lshl_add_u64 v[6:7], v[66:67], 0, s[8:9]
	global_load_lds_dwordx4 v[66:67], off
	s_mov_b32 m0, s79
	v_readfirstlane_b32 s77, v115
	global_load_lds_dwordx4 v[6:7], off
	v_lshl_add_u64 v[0:1], v[64:65], 0, s[10:11]
	s_mov_b32 m0, s77
	v_readfirstlane_b32 s0, v136
	global_load_lds_dwordx4 v[0:1], off
	v_lshl_add_u64 v[0:1], v[64:65], 0, s[12:13]
	s_mov_b32 m0, s0
	s_mov_b64 s[4:5], 0x40080
	global_load_lds_dwordx4 v[0:1], off
	v_lshl_add_u64 v[0:1], v[64:65], 0, s[4:5]
	v_readfirstlane_b32 s4, v137
	s_mov_b32 m0, s4
	s_mov_b64 s[4:5], 0x60080
	global_load_lds_dwordx4 v[0:1], off
	v_lshl_add_u64 v[0:1], v[64:65], 0, s[4:5]
	v_readfirstlane_b32 s4, v138
	s_mov_b32 m0, s4
	v_readfirstlane_b32 s4, v139
	global_load_lds_dwordx4 v[0:1], off
	v_lshl_add_u64 v[0:1], v[66:67], 0, s[10:11]
	s_mov_b32 m0, s4
	v_readfirstlane_b32 s4, v144
	global_load_lds_dwordx4 v[0:1], off
	v_lshl_add_u64 v[0:1], v[66:67], 0, s[12:13]
	s_mov_b32 m0, s4
	v_readfirstlane_b32 s4, v117
	global_load_lds_dwordx4 v[0:1], off
	s_waitcnt vmcnt(6)
	s_waitcnt lgkmcnt(0)
	s_barrier
	v_lshl_add_u64 v[0:1], v[64:65], 0, s[14:15]
	s_mov_b32 m0, s4
	v_readfirstlane_b32 s91, v119
	global_load_lds_dwordx4 v[0:1], off
	v_lshl_add_u64 v[0:1], v[64:65], 0, s[16:17]
	s_mov_b32 m0, s91
	s_mov_b64 s[46:47], 0x40100
	v_readfirstlane_b32 s89, v121
	global_load_lds_dwordx4 v[0:1], off
	v_lshl_add_u64 v[0:1], v[64:65], 0, s[46:47]
	s_mov_b32 m0, s89
	s_mov_b64 s[46:47], 0x60100
	v_readfirstlane_b32 s90, v124
	global_load_lds_dwordx4 v[0:1], off
	v_lshl_add_u64 v[0:1], v[64:65], 0, s[46:47]
	s_mov_b32 m0, s90
	v_readfirstlane_b32 s47, v125
	global_load_lds_dwordx4 v[0:1], off
	v_lshl_add_u64 v[0:1], v[66:67], 0, s[14:15]
	s_mov_b32 m0, s47
	v_readfirstlane_b32 s88, v126
	global_load_lds_dwordx4 v[0:1], off
	v_lshl_add_u64 v[0:1], v[66:67], 0, s[16:17]
	s_mov_b32 m0, s88
	s_nop 0
	global_load_lds_dwordx4 v[0:1], off
	ds_read_b128 v[0:3], v145 offset:32768
	ds_read_b128 v[4:7], v145 offset:36864
	ds_read_b128 v[8:11], v146
	ds_read_b128 v[12:15], v146 offset:4096
	ds_read_b128 v[68:71], v147 offset:32768
	ds_read_b128 v[72:75], v147 offset:36864
	ds_read_b128 v[76:79], v148
	ds_read_b128 v[80:83], v148 offset:4096
	s_mov_b32 m0, s6
	s_mov_b64 s[86:87], 0x40180
	s_waitcnt lgkmcnt(0)
	v_mfma_f32_32x32x16_bf16 v[48:63], v[0:3], v[8:11], 0
	v_mfma_f32_32x32x16_bf16 v[16:31], v[0:3], v[12:15], 0
	v_mfma_f32_32x32x16_bf16 v[32:47], v[4:7], v[8:11], 0
	v_mfma_f32_32x32x16_bf16 v[0:15], v[4:7], v[12:15], 0
	ds_read_b128 v[184:187], v149 offset:32768
	ds_read_b128 v[188:191], v149 offset:36864
	ds_read_b128 v[192:195], v150
	ds_read_b128 v[196:199], v150 offset:4096
	s_waitcnt lgkmcnt(4)
	v_mfma_f32_32x32x16_bf16 v[48:63], v[68:71], v[76:79], v[48:63]
	v_mfma_f32_32x32x16_bf16 v[16:31], v[68:71], v[80:83], v[16:31]
	v_mfma_f32_32x32x16_bf16 v[32:47], v[72:75], v[76:79], v[32:47]
	v_mfma_f32_32x32x16_bf16 v[0:15], v[72:75], v[80:83], v[0:15]
	ds_read_b128 v[68:71], v151 offset:32768
	ds_read_b128 v[72:75], v151 offset:36864
	ds_read_b128 v[76:79], v152
	ds_read_b128 v[80:83], v152 offset:4096
	s_waitcnt lgkmcnt(4)
	v_mfma_f32_32x32x16_bf16 v[48:63], v[184:187], v[192:195], v[48:63]
	v_mfma_f32_32x32x16_bf16 v[16:31], v[184:187], v[196:199], v[16:31]
	v_mfma_f32_32x32x16_bf16 v[32:47], v[188:191], v[192:195], v[32:47]
	v_mfma_f32_32x32x16_bf16 v[0:15], v[188:191], v[196:199], v[0:15]
	s_waitcnt vmcnt(6)
	s_waitcnt lgkmcnt(0)
	s_barrier
; #define MFMA(a, b, c) __builtin_amdgcn_mfma_f32_32x32x16_bf16((a), (b), (c), 0, 0, 0)
; #define WAIT_V(n) asm volatile("s_waitcnt vmcnt(%0)" ::"n"(n) : "memory")
; #define RAW_BARRIER() do { asm volatile("s_waitcnt lgkmcnt(0)" ::: "memory"); __builtin_amdgcn_s_barrier(); asm volatile("" ::: "memory"); } while (0)
; #define GLDS_STAGE(slot, kt) do { _Pragma("unroll") for (int i = 0; i < 6; ++i) \
;     __builtin_amdgcn_global_load_lds((const unsigned*)(src[i] + (kt) * 64), (__attribute__((address_space(3))) unsigned*)(smem + (slot) * G_STAGE + (wave + 8 * i) * 1024), 16, 0, 0); } while (0)
; DI void gemm_tile(const u16* __restrict__ X, int ldx, const u16* __restrict__ Wt, int ldw, int K, char* smem,
;                   f32x16 (&acc)[2][2]) {
;     ...
;   for (int kt = 0; kt < nk; ++kt) {
;     const int nxt = (cur >= 1) ? cur - 1 : 2;
;     if (kt + 2 < nk) GLDS_STAGE(nxt, kt + 2);
;     __builtin_amdgcn_sched_barrier(0);
;     const char* st = smem + cur * G_STAGE;
; #pragma unroll
;     for (int ks = 0; ks < 4; ++ks) {
;       bf16x8 a[2], b[2];
; #pragma unroll
;       for (int ft = 0; ft < 2; ++ft) a[ft] = *reinterpret_cast<const bf16x8*>(st + offA[ft] + (((ks * 2 + lh) ^ xa[ft]) << 4));
; #pragma unroll
;       for (int tt = 0; tt < 2; ++tt) b[tt] = *reinterpret_cast<const bf16x8*>(st + offB[tt] + (((ks * 2 + lh) ^ xb[tt]) << 4));
; #pragma unroll
;       for (int ft = 0; ft < 2; ++ft)
; #pragma unroll
;         for (int tt = 0; tt < 2; ++tt) acc[ft][tt] = MFMA(a[ft], b[tt], acc[ft][tt]);
;     }
;     if (kt + 2 < nk) { WAIT_V(6); } else { WAIT_V(0); }
;     RAW_BARRIER();
;     cur = (cur == 2) ? 0 : cur + 1;
;   }
	ds_read_b128 v[184:187], v153 offset:32768
	ds_read_b128 v[188:191], v153 offset:36864
	ds_read_b128 v[192:195], v146 offset:49152
	ds_read_b128 v[196:199], v146 offset:53248
	s_waitcnt lgkmcnt(4)
	v_mfma_f32_32x32x16_bf16 v[48:63], v[68:71], v[76:79], v[48:63]
	v_mfma_f32_32x32x16_bf16 v[16:31], v[68:71], v[80:83], v[16:31]
	v_lshl_add_u64 v[68:69], v[64:65], 0, s[18:19]
	global_load_lds_dwordx4 v[68:69], off
	v_lshl_add_u64 v[68:69], v[64:65], 0, s[20:21]
	s_mov_b32 m0, s85
	s_nop 0
	global_load_lds_dwordx4 v[68:69], off
	v_lshl_add_u64 v[68:69], v[64:65], 0, s[86:87]
	s_mov_b32 m0, s84
	s_mov_b64 s[86:87], 0x60180
	global_load_lds_dwordx4 v[68:69], off
	v_lshl_add_u64 v[68:69], v[64:65], 0, s[86:87]
	s_mov_b32 m0, s81
	v_mfma_f32_32x32x16_bf16 v[32:47], v[72:75], v[76:79], v[32:47]
	global_load_lds_dwordx4 v[68:69], off
	v_lshl_add_u64 v[68:69], v[66:67], 0, s[18:19]
	s_mov_b32 m0, s80
	s_nop 0
	global_load_lds_dwordx4 v[68:69], off
	v_lshl_add_u64 v[68:69], v[66:67], 0, s[20:21]
	s_mov_b32 m0, s79
	v_mfma_f32_32x32x16_bf16 v[0:15], v[72:75], v[80:83], v[0:15]
	global_load_lds_dwordx4 v[68:69], off
	s_mov_b32 m0, s77
	s_mov_b64 s[86:87], 0x40200
	v_readfirstlane_b32 s7, v127
	ds_read_b128 v[68:71], v154 offset:32768
	ds_read_b128 v[72:75], v154 offset:36864
	ds_read_b128 v[76:79], v148 offset:49152
	ds_read_b128 v[80:83], v148 offset:53248
	s_waitcnt lgkmcnt(4)
	v_mfma_f32_32x32x16_bf16 v[48:63], v[184:187], v[192:195], v[48:63]
	v_readfirstlane_b32 s46, v130
	v_mfma_f32_32x32x16_bf16 v[16:31], v[184:187], v[196:199], v[16:31]
	v_mfma_f32_32x32x16_bf16 v[32:47], v[188:191], v[192:195], v[32:47]
	v_mfma_f32_32x32x16_bf16 v[0:15], v[188:191], v[196:199], v[0:15]
	ds_read_b128 v[184:187], v155 offset:32768
	ds_read_b128 v[188:191], v155 offset:36864
	ds_read_b128 v[192:195], v150 offset:49152
	ds_read_b128 v[196:199], v150 offset:53248
	s_waitcnt lgkmcnt(4)
	v_mfma_f32_32x32x16_bf16 v[48:63], v[68:71], v[76:79], v[48:63]
	v_mfma_f32_32x32x16_bf16 v[16:31], v[68:71], v[80:83], v[16:31]
	v_mfma_f32_32x32x16_bf16 v[32:47], v[72:75], v[76:79], v[32:47]
	v_mfma_f32_32x32x16_bf16 v[0:15], v[72:75], v[80:83], v[0:15]
	ds_read_b128 v[68:71], v156 offset:32768
	ds_read_b128 v[72:75], v156 offset:36864
	ds_read_b128 v[76:79], v152 offset:49152
	ds_read_b128 v[80:83], v152 offset:53248
	s_waitcnt lgkmcnt(4)
	v_mfma_f32_32x32x16_bf16 v[48:63], v[184:187], v[192:195], v[48:63]
	v_mfma_f32_32x32x16_bf16 v[16:31], v[184:187], v[196:199], v[16:31]
	v_mfma_f32_32x32x16_bf16 v[32:47], v[188:191], v[192:195], v[32:47]
	v_mfma_f32_32x32x16_bf16 v[0:15], v[188:191], v[196:199], v[0:15]
	s_waitcnt vmcnt(6)
	s_waitcnt lgkmcnt(0)
	s_barrier
	ds_read_b128 v[184:187], v157 offset:32768
	ds_read_b128 v[188:191], v157 offset:36864
	ds_read_b128 v[192:195], v158
	ds_read_b128 v[196:199], v158 offset:4096
	s_waitcnt lgkmcnt(4)
	v_mfma_f32_32x32x16_bf16 v[48:63], v[68:71], v[76:79], v[48:63]
	v_mfma_f32_32x32x16_bf16 v[16:31], v[68:71], v[80:83], v[16:31]
	v_lshl_add_u64 v[68:69], v[64:65], 0, s[22:23]
	global_load_lds_dwordx4 v[68:69], off
	v_lshl_add_u64 v[68:69], v[64:65], 0, s[24:25]
	s_mov_b32 m0, s0
	s_nop 0
	global_load_lds_dwordx4 v[68:69], off
	v_lshl_add_u64 v[68:69], v[64:65], 0, s[86:87]
	s_mov_b32 m0, s7
	s_mov_b64 s[86:87], 0x60200
	global_load_lds_dwordx4 v[68:69], off
	v_lshl_add_u64 v[68:69], v[64:65], 0, s[86:87]
	v_readfirstlane_b32 s87, v128
	s_mov_b32 m0, s87
	v_readfirstlane_b32 s86, v129
	global_load_lds_dwordx4 v[68:69], off
	v_lshl_add_u64 v[68:69], v[66:67], 0, s[22:23]
	s_mov_b32 m0, s86
	v_mfma_f32_32x32x16_bf16 v[32:47], v[72:75], v[76:79], v[32:47]
	global_load_lds_dwordx4 v[68:69], off
	v_lshl_add_u64 v[68:69], v[66:67], 0, s[24:25]
	s_mov_b32 m0, s46
	s_nop 0
	global_load_lds_dwordx4 v[68:69], off
	v_mfma_f32_32x32x16_bf16 v[0:15], v[72:75], v[80:83], v[0:15]
	s_mov_b32 m0, s4
	s_mov_b64 s[92:93], 0x40280
	ds_read_b128 v[68:71], v159 offset:32768
	ds_read_b128 v[72:75], v159 offset:36864
	ds_read_b128 v[76:79], v160
	ds_read_b128 v[80:83], v160 offset:4096
	s_waitcnt lgkmcnt(4)
	v_mfma_f32_32x32x16_bf16 v[48:63], v[184:187], v[192:195], v[48:63]
	v_mfma_f32_32x32x16_bf16 v[16:31], v[184:187], v[196:199], v[16:31]
	v_mfma_f32_32x32x16_bf16 v[32:47], v[188:191], v[192:195], v[32:47]
	v_mfma_f32_32x32x16_bf16 v[0:15], v[188:191], v[196:199], v[0:15]
	ds_read_b128 v[184:187], v161 offset:32768
	ds_read_b128 v[188:191], v161 offset:36864
	ds_read_b128 v[192:195], v163
	ds_read_b128 v[196:199], v163 offset:4096
	s_waitcnt lgkmcnt(4)
	v_mfma_f32_32x32x16_bf16 v[48:63], v[68:71], v[76:79], v[48:63]
	v_mfma_f32_32x32x16_bf16 v[16:31], v[68:71], v[80:83], v[16:31]
	v_mfma_f32_32x32x16_bf16 v[32:47], v[72:75], v[76:79], v[32:47]
	v_mfma_f32_32x32x16_bf16 v[0:15], v[72:75], v[80:83], v[0:15]
	ds_read_b128 v[68:71], v165 offset:32768
	ds_read_b128 v[72:75], v165 offset:36864
	ds_read_b128 v[76:79], v167
	ds_read_b128 v[80:83], v167 offset:4096
	s_waitcnt lgkmcnt(4)
	v_mfma_f32_32x32x16_bf16 v[48:63], v[184:187], v[192:195], v[48:63]
	v_mfma_f32_32x32x16_bf16 v[16:31], v[184:187], v[196:199], v[16:31]
	v_mfma_f32_32x32x16_bf16 v[32:47], v[188:191], v[192:195], v[32:47]
	v_mfma_f32_32x32x16_bf16 v[0:15], v[188:191], v[196:199], v[0:15]
	s_waitcnt vmcnt(6)
	s_waitcnt lgkmcnt(0)
	s_barrier
; #define MFMA(a, b, c) __builtin_amdgcn_mfma_f32_32x32x16_bf16((a), (b), (c), 0, 0, 0)
; #define WAIT_V(n) asm volatile("s_waitcnt vmcnt(%0)" ::"n"(n) : "memory")
; #define RAW_BARRIER() do { asm volatile("s_waitcnt lgkmcnt(0)" ::: "memory"); __builtin_amdgcn_s_barrier(); asm volatile("" ::: "memory"); } while (0)
; #define GLDS_STAGE(slot, kt) do { _Pragma("unroll") for (int i = 0; i < 6; ++i) \
;     __builtin_amdgcn_global_load_lds((const unsigned*)(src[i] + (kt) * 64), (__attribute__((address_space(3))) unsigned*)(smem + (slot) * G_STAGE + (wave + 8 * i) * 1024), 16, 0, 0); } while (0)
; DI void gemm_tile(const u16* __restrict__ X, int ldx, const u16* __restrict__ Wt, int ldw, int K, char* smem,
;                   f32x16 (&acc)[2][2]) {
;     ...
;   for (int kt = 0; kt < nk; ++kt) {
;     const int nxt = (cur >= 1) ? cur - 1 : 2;
;     if (kt + 2 < nk) GLDS_STAGE(nxt, kt + 2);
;     __builtin_amdgcn_sched_barrier(0);
;     const char* st = smem + cur * G_STAGE;
; #pragma unroll
;     for (int ks = 0; ks < 4; ++ks) {
;       bf16x8 a[2], b[2];
; #pragma unroll
;       for (int ft = 0; ft < 2; ++ft) a[ft] = *reinterpret_cast<const bf16x8*>(st + offA[ft] + (((ks * 2 + lh) ^ xa[ft]) << 4));
; #pragma unroll
;       for (int tt = 0; tt < 2; ++tt) b[tt] = *reinterpret_cast<const bf16x8*>(st + offB[tt] + (((ks * 2 + lh) ^ xb[tt]) << 4));
; #pragma unroll
;       for (int ft = 0; ft < 2; ++ft)
; #pragma unroll
;         for (int tt = 0; tt < 2; ++tt) acc[ft][tt] = MFMA(a[ft], b[tt], acc[ft][tt]);
;     }
;     if (kt + 2 < nk) { WAIT_V(6); } else { WAIT_V(0); }
;     RAW_BARRIER();
;     cur = (cur == 2) ? 0 : cur + 1;
;   }
	ds_read_b128 v[184:187], v145 offset:32768
	ds_read_b128 v[188:191], v145 offset:36864
	ds_read_b128 v[192:195], v146
	ds_read_b128 v[196:199], v146 offset:4096
	s_waitcnt lgkmcnt(4)
	v_mfma_f32_32x32x16_bf16 v[48:63], v[68:71], v[76:79], v[48:63]
	v_mfma_f32_32x32x16_bf16 v[16:31], v[68:71], v[80:83], v[16:31]
	v_lshl_add_u64 v[68:69], v[64:65], 0, s[26:27]
	global_load_lds_dwordx4 v[68:69], off
	v_lshl_add_u64 v[68:69], v[64:65], 0, s[28:29]
	s_mov_b32 m0, s91
	s_nop 0
	global_load_lds_dwordx4 v[68:69], off
	v_lshl_add_u64 v[68:69], v[64:65], 0, s[92:93]
	s_mov_b32 m0, s89
	s_mov_b64 s[92:93], 0x60280
	global_load_lds_dwordx4 v[68:69], off
	v_lshl_add_u64 v[68:69], v[64:65], 0, s[92:93]
	s_mov_b32 m0, s90
	v_mfma_f32_32x32x16_bf16 v[32:47], v[72:75], v[76:79], v[32:47]
	global_load_lds_dwordx4 v[68:69], off
	v_lshl_add_u64 v[68:69], v[66:67], 0, s[26:27]
	s_mov_b32 m0, s47
	s_nop 0
	global_load_lds_dwordx4 v[68:69], off
	v_lshl_add_u64 v[68:69], v[66:67], 0, s[28:29]
	s_mov_b32 m0, s88
	v_mfma_f32_32x32x16_bf16 v[0:15], v[72:75], v[80:83], v[0:15]
	global_load_lds_dwordx4 v[68:69], off
	s_mov_b32 m0, s6
	s_mov_b64 s[92:93], 0x40300
	ds_read_b128 v[68:71], v147 offset:32768
	ds_read_b128 v[72:75], v147 offset:36864
	ds_read_b128 v[76:79], v148
	ds_read_b128 v[80:83], v148 offset:4096
	s_waitcnt lgkmcnt(4)
	v_mfma_f32_32x32x16_bf16 v[48:63], v[184:187], v[192:195], v[48:63]
	v_mfma_f32_32x32x16_bf16 v[16:31], v[184:187], v[196:199], v[16:31]
	v_mfma_f32_32x32x16_bf16 v[32:47], v[188:191], v[192:195], v[32:47]
	v_mfma_f32_32x32x16_bf16 v[0:15], v[188:191], v[196:199], v[0:15]
	ds_read_b128 v[184:187], v149 offset:32768
	ds_read_b128 v[188:191], v149 offset:36864
	ds_read_b128 v[192:195], v150
	ds_read_b128 v[196:199], v150 offset:4096
	s_waitcnt lgkmcnt(4)
	v_mfma_f32_32x32x16_bf16 v[48:63], v[68:71], v[76:79], v[48:63]
	v_mfma_f32_32x32x16_bf16 v[16:31], v[68:71], v[80:83], v[16:31]
	v_mfma_f32_32x32x16_bf16 v[32:47], v[72:75], v[76:79], v[32:47]
	v_mfma_f32_32x32x16_bf16 v[0:15], v[72:75], v[80:83], v[0:15]
	ds_read_b128 v[68:71], v151 offset:32768
	ds_read_b128 v[72:75], v151 offset:36864
	ds_read_b128 v[76:79], v152
	ds_read_b128 v[80:83], v152 offset:4096
	s_waitcnt lgkmcnt(4)
	v_mfma_f32_32x32x16_bf16 v[48:63], v[184:187], v[192:195], v[48:63]
	v_mfma_f32_32x32x16_bf16 v[16:31], v[184:187], v[196:199], v[16:31]
	v_mfma_f32_32x32x16_bf16 v[32:47], v[188:191], v[192:195], v[32:47]
	v_mfma_f32_32x32x16_bf16 v[0:15], v[188:191], v[196:199], v[0:15]
	s_waitcnt vmcnt(6)
	s_waitcnt lgkmcnt(0)
	s_barrier
	ds_read_b128 v[184:187], v153 offset:32768
	ds_read_b128 v[188:191], v153 offset:36864
	ds_read_b128 v[192:195], v146 offset:49152
	ds_read_b128 v[196:199], v146 offset:53248
	s_waitcnt lgkmcnt(4)
	v_mfma_f32_32x32x16_bf16 v[48:63], v[68:71], v[76:79], v[48:63]
	v_mfma_f32_32x32x16_bf16 v[16:31], v[68:71], v[80:83], v[16:31]
	v_lshl_add_u64 v[68:69], v[64:65], 0, s[30:31]
	global_load_lds_dwordx4 v[68:69], off
	v_lshl_add_u64 v[68:69], v[64:65], 0, s[34:35]
	s_mov_b32 m0, s85
	s_nop 0
	global_load_lds_dwordx4 v[68:69], off
	v_lshl_add_u64 v[68:69], v[64:65], 0, s[92:93]
	s_mov_b32 m0, s84
	s_mov_b64 s[92:93], 0x60300
	global_load_lds_dwordx4 v[68:69], off
	v_lshl_add_u64 v[68:69], v[64:65], 0, s[92:93]
	s_mov_b32 m0, s81
	v_mfma_f32_32x32x16_bf16 v[32:47], v[72:75], v[76:79], v[32:47]
	global_load_lds_dwordx4 v[68:69], off
	v_lshl_add_u64 v[68:69], v[66:67], 0, s[30:31]
	s_mov_b32 m0, s80
	s_nop 0
	global_load_lds_dwordx4 v[68:69], off
	v_lshl_add_u64 v[68:69], v[66:67], 0, s[34:35]
	s_mov_b32 m0, s79
	v_mfma_f32_32x32x16_bf16 v[0:15], v[72:75], v[80:83], v[0:15]
	global_load_lds_dwordx4 v[68:69], off
	s_mov_b32 m0, s77
	s_mov_b64 s[92:93], 0x40380
	ds_read_b128 v[68:71], v154 offset:32768
	ds_read_b128 v[72:75], v154 offset:36864
	ds_read_b128 v[76:79], v148 offset:49152
	ds_read_b128 v[80:83], v148 offset:53248
	s_waitcnt lgkmcnt(4)
	v_mfma_f32_32x32x16_bf16 v[48:63], v[184:187], v[192:195], v[48:63]
	v_mfma_f32_32x32x16_bf16 v[16:31], v[184:187], v[196:199], v[16:31]
	v_mfma_f32_32x32x16_bf16 v[32:47], v[188:191], v[192:195], v[32:47]
	v_mfma_f32_32x32x16_bf16 v[0:15], v[188:191], v[196:199], v[0:15]
	ds_read_b128 v[184:187], v155 offset:32768
	ds_read_b128 v[188:191], v155 offset:36864
	ds_read_b128 v[192:195], v150 offset:49152
	ds_read_b128 v[196:199], v150 offset:53248
	s_waitcnt lgkmcnt(4)
	v_mfma_f32_32x32x16_bf16 v[48:63], v[68:71], v[76:79], v[48:63]
	v_mfma_f32_32x32x16_bf16 v[16:31], v[68:71], v[80:83], v[16:31]
	v_mfma_f32_32x32x16_bf16 v[32:47], v[72:75], v[76:79], v[32:47]
	v_mfma_f32_32x32x16_bf16 v[0:15], v[72:75], v[80:83], v[0:15]
	ds_read_b128 v[68:71], v156 offset:32768
	ds_read_b128 v[72:75], v156 offset:36864
	ds_read_b128 v[76:79], v152 offset:49152
	ds_read_b128 v[80:83], v152 offset:53248
	s_waitcnt lgkmcnt(4)
	v_mfma_f32_32x32x16_bf16 v[48:63], v[184:187], v[192:195], v[48:63]
	v_mfma_f32_32x32x16_bf16 v[16:31], v[184:187], v[196:199], v[16:31]
	v_mfma_f32_32x32x16_bf16 v[32:47], v[188:191], v[192:195], v[32:47]
	v_mfma_f32_32x32x16_bf16 v[0:15], v[188:191], v[196:199], v[0:15]
	s_waitcnt vmcnt(6)
	s_waitcnt lgkmcnt(0)
	s_barrier
; #define MFMA(a, b, c) __builtin_amdgcn_mfma_f32_32x32x16_bf16((a), (b), (c), 0, 0, 0)
; #define WAIT_V(n) asm volatile("s_waitcnt vmcnt(%0)" ::"n"(n) : "memory")
; #define RAW_BARRIER() do { asm volatile("s_waitcnt lgkmcnt(0)" ::: "memory"); __builtin_amdgcn_s_barrier(); asm volatile("" ::: "memory"); } while (0)
; #define GLDS_STAGE(slot, kt) do { _Pragma("unroll") for (int i = 0; i < 6; ++i) \
;     __builtin_amdgcn_global_load_lds((const unsigned*)(src[i] + (kt) * 64), (__attribute__((address_space(3))) unsigned*)(smem + (slot) * G_STAGE + (wave + 8 * i) * 1024), 16, 0, 0); } while (0)
; DI void gemm_tile(const u16* __restrict__ X, int ldx, const u16* __restrict__ Wt, int ldw, int K, char* smem,
;                   f32x16 (&acc)[2][2]) {
;     ...
;   for (int kt = 0; kt < nk; ++kt) {
;     const int nxt = (cur >= 1) ? cur - 1 : 2;
;     if (kt + 2 < nk) GLDS_STAGE(nxt, kt + 2);
;     __builtin_amdgcn_sched_barrier(0);
;     const char* st = smem + cur * G_STAGE;
; #pragma unroll
;     for (int ks = 0; ks < 4; ++ks) {
;       bf16x8 a[2], b[2];
; #pragma unroll
;       for (int ft = 0; ft < 2; ++ft) a[ft] = *reinterpret_cast<const bf16x8*>(st + offA[ft] + (((ks * 2 + lh) ^ xa[ft]) << 4));
; #pragma unroll
;       for (int tt = 0; tt < 2; ++tt) b[tt] = *reinterpret_cast<const bf16x8*>(st + offB[tt] + (((ks * 2 + lh) ^ xb[tt]) << 4));
; #pragma unroll
;       for (int ft = 0; ft < 2; ++ft)
; #pragma unroll
;         for (int tt = 0; tt < 2; ++tt) acc[ft][tt] = MFMA(a[ft], b[tt], acc[ft][tt]);
;     }
;     if (kt + 2 < nk) { WAIT_V(6); } else { WAIT_V(0); }
;     RAW_BARRIER();
;     cur = (cur == 2) ? 0 : cur + 1;
;   }
	ds_read_b128 v[184:187], v157 offset:32768
	ds_read_b128 v[188:191], v157 offset:36864
	ds_read_b128 v[192:195], v158
	ds_read_b128 v[196:199], v158 offset:4096
	s_waitcnt lgkmcnt(4)
	v_mfma_f32_32x32x16_bf16 v[48:63], v[68:71], v[76:79], v[48:63]
	v_mfma_f32_32x32x16_bf16 v[16:31], v[68:71], v[80:83], v[16:31]
	v_lshl_add_u64 v[68:69], v[64:65], 0, s[36:37]
	global_load_lds_dwordx4 v[68:69], off
	v_lshl_add_u64 v[68:69], v[64:65], 0, s[38:39]
	s_mov_b32 m0, s0
	s_nop 0
	global_load_lds_dwordx4 v[68:69], off
	v_lshl_add_u64 v[68:69], v[64:65], 0, s[92:93]
	s_mov_b32 m0, s7
	s_mov_b64 s[92:93], 0x60380
	global_load_lds_dwordx4 v[68:69], off
	v_lshl_add_u64 v[68:69], v[64:65], 0, s[92:93]
	s_mov_b32 m0, s87
	v_mfma_f32_32x32x16_bf16 v[32:47], v[72:75], v[76:79], v[32:47]
	global_load_lds_dwordx4 v[68:69], off
	v_lshl_add_u64 v[68:69], v[66:67], 0, s[36:37]
	s_mov_b32 m0, s86
	s_nop 0
	global_load_lds_dwordx4 v[68:69], off
	v_lshl_add_u64 v[68:69], v[66:67], 0, s[38:39]
	s_mov_b32 m0, s46
	v_mfma_f32_32x32x16_bf16 v[0:15], v[72:75], v[80:83], v[0:15]
	global_load_lds_dwordx4 v[68:69], off
	s_mov_b32 m0, s4
	s_mov_b64 s[4:5], 0x40400
	ds_read_b128 v[68:71], v159 offset:32768
	ds_read_b128 v[72:75], v159 offset:36864
	ds_read_b128 v[76:79], v160
	ds_read_b128 v[80:83], v160 offset:4096
	s_waitcnt lgkmcnt(4)
	v_mfma_f32_32x32x16_bf16 v[48:63], v[184:187], v[192:195], v[48:63]
	v_mfma_f32_32x32x16_bf16 v[16:31], v[184:187], v[196:199], v[16:31]
	v_mfma_f32_32x32x16_bf16 v[32:47], v[188:191], v[192:195], v[32:47]
	v_mfma_f32_32x32x16_bf16 v[0:15], v[188:191], v[196:199], v[0:15]
	ds_read_b128 v[184:187], v161 offset:32768
	ds_read_b128 v[188:191], v161 offset:36864
	ds_read_b128 v[192:195], v163
	ds_read_b128 v[196:199], v163 offset:4096
	s_waitcnt lgkmcnt(4)
	v_mfma_f32_32x32x16_bf16 v[48:63], v[68:71], v[76:79], v[48:63]
	v_mfma_f32_32x32x16_bf16 v[16:31], v[68:71], v[80:83], v[16:31]
	v_mfma_f32_32x32x16_bf16 v[32:47], v[72:75], v[76:79], v[32:47]
	v_mfma_f32_32x32x16_bf16 v[0:15], v[72:75], v[80:83], v[0:15]
	ds_read_b128 v[68:71], v165 offset:32768
	ds_read_b128 v[72:75], v165 offset:36864
	ds_read_b128 v[76:79], v167
	ds_read_b128 v[80:83], v167 offset:4096
	s_waitcnt lgkmcnt(4)
	v_mfma_f32_32x32x16_bf16 v[48:63], v[184:187], v[192:195], v[48:63]
	v_mfma_f32_32x32x16_bf16 v[16:31], v[184:187], v[196:199], v[16:31]
	v_mfma_f32_32x32x16_bf16 v[32:47], v[188:191], v[192:195], v[32:47]
	v_mfma_f32_32x32x16_bf16 v[0:15], v[188:191], v[196:199], v[0:15]
	s_waitcnt vmcnt(6)
	s_waitcnt lgkmcnt(0)
	s_barrier
	ds_read_b128 v[184:187], v145 offset:32768
	ds_read_b128 v[188:191], v145 offset:36864
	ds_read_b128 v[192:195], v146
	ds_read_b128 v[196:199], v146 offset:4096
	s_waitcnt lgkmcnt(4)
	v_mfma_f32_32x32x16_bf16 v[48:63], v[68:71], v[76:79], v[48:63]
	v_mfma_f32_32x32x16_bf16 v[16:31], v[68:71], v[80:83], v[16:31]
	v_lshl_add_u64 v[68:69], v[64:65], 0, s[40:41]
	global_load_lds_dwordx4 v[68:69], off
	v_lshl_add_u64 v[68:69], v[64:65], 0, s[42:43]
	s_mov_b32 m0, s91
	s_nop 0
	global_load_lds_dwordx4 v[68:69], off
	v_lshl_add_u64 v[68:69], v[64:65], 0, s[4:5]
	s_mov_b32 m0, s89
	s_mov_b64 s[4:5], 0x60400
	global_load_lds_dwordx4 v[68:69], off
	v_lshl_add_u64 v[68:69], v[64:65], 0, s[4:5]
	s_mov_b32 m0, s90
	v_mfma_f32_32x32x16_bf16 v[32:47], v[72:75], v[76:79], v[32:47]
	global_load_lds_dwordx4 v[68:69], off
	v_lshl_add_u64 v[68:69], v[66:67], 0, s[40:41]
	s_mov_b32 m0, s47
	s_nop 0
	global_load_lds_dwordx4 v[68:69], off
	v_lshl_add_u64 v[68:69], v[66:67], 0, s[42:43]
	s_mov_b32 m0, s88
	v_mfma_f32_32x32x16_bf16 v[0:15], v[72:75], v[80:83], v[0:15]
	global_load_lds_dwordx4 v[68:69], off
	s_mov_b32 m0, s6
	s_mov_b64 s[4:5], 0x40480
	ds_read_b128 v[68:71], v147 offset:32768
	ds_read_b128 v[72:75], v147 offset:36864
	ds_read_b128 v[76:79], v148
	ds_read_b128 v[80:83], v148 offset:4096
	s_waitcnt lgkmcnt(4)
	v_mfma_f32_32x32x16_bf16 v[48:63], v[184:187], v[192:195], v[48:63]
	v_mfma_f32_32x32x16_bf16 v[16:31], v[184:187], v[196:199], v[16:31]
	v_mfma_f32_32x32x16_bf16 v[32:47], v[188:191], v[192:195], v[32:47]
	v_mfma_f32_32x32x16_bf16 v[0:15], v[188:191], v[196:199], v[0:15]
	ds_read_b128 v[184:187], v149 offset:32768
	ds_read_b128 v[188:191], v149 offset:36864
	ds_read_b128 v[192:195], v150
	ds_read_b128 v[196:199], v150 offset:4096
	s_waitcnt lgkmcnt(4)
	v_mfma_f32_32x32x16_bf16 v[48:63], v[68:71], v[76:79], v[48:63]
	v_mfma_f32_32x32x16_bf16 v[16:31], v[68:71], v[80:83], v[16:31]
	v_mfma_f32_32x32x16_bf16 v[32:47], v[72:75], v[76:79], v[32:47]
	v_mfma_f32_32x32x16_bf16 v[0:15], v[72:75], v[80:83], v[0:15]
	ds_read_b128 v[68:71], v151 offset:32768
	ds_read_b128 v[72:75], v151 offset:36864
	ds_read_b128 v[76:79], v152
	ds_read_b128 v[80:83], v152 offset:4096
	s_waitcnt lgkmcnt(4)
	v_mfma_f32_32x32x16_bf16 v[48:63], v[184:187], v[192:195], v[48:63]
	v_mfma_f32_32x32x16_bf16 v[16:31], v[184:187], v[196:199], v[16:31]
	v_mfma_f32_32x32x16_bf16 v[32:47], v[188:191], v[192:195], v[32:47]
	v_mfma_f32_32x32x16_bf16 v[0:15], v[188:191], v[196:199], v[0:15]
	s_waitcnt vmcnt(6)
	s_waitcnt lgkmcnt(0)
	s_barrier
; #define MFMA(a, b, c) __builtin_amdgcn_mfma_f32_32x32x16_bf16((a), (b), (c), 0, 0, 0)
; #define WAIT_V(n) asm volatile("s_waitcnt vmcnt(%0)" ::"n"(n) : "memory")
; #define RAW_BARRIER() do { asm volatile("s_waitcnt lgkmcnt(0)" ::: "memory"); __builtin_amdgcn_s_barrier(); asm volatile("" ::: "memory"); } while (0)
; #define GLDS_STAGE(slot, kt) do { _Pragma("unroll") for (int i = 0; i < 6; ++i) \
;     __builtin_amdgcn_global_load_lds((const unsigned*)(src[i] + (kt) * 64), (__attribute__((address_space(3))) unsigned*)(smem + (slot) * G_STAGE + (wave + 8 * i) * 1024), 16, 0, 0); } while (0)
; DI void gemm_tile(const u16* __restrict__ X, int ldx, const u16* __restrict__ Wt, int ldw, int K, char* smem,
;                   f32x16 (&acc)[2][2]) {
;     ...
;   for (int kt = 0; kt < nk; ++kt) {
;     const int nxt = (cur >= 1) ? cur - 1 : 2;
;     if (kt + 2 < nk) GLDS_STAGE(nxt, kt + 2);
;     __builtin_amdgcn_sched_barrier(0);
;     const char* st = smem + cur * G_STAGE;
; #pragma unroll
;     for (int ks = 0; ks < 4; ++ks) {
;       bf16x8 a[2], b[2];
; #pragma unroll
;       for (int ft = 0; ft < 2; ++ft) a[ft] = *reinterpret_cast<const bf16x8*>(st + offA[ft] + (((ks * 2 + lh) ^ xa[ft]) << 4));
; #pragma unroll
;       for (int tt = 0; tt < 2; ++tt) b[tt] = *reinterpret_cast<const bf16x8*>(st + offB[tt] + (((ks * 2 + lh) ^ xb[tt]) << 4));
; #pragma unroll
;       for (int ft = 0; ft < 2; ++ft)
; #pragma unroll
;         for (int tt = 0; tt < 2; ++tt) acc[ft][tt] = MFMA(a[ft], b[tt], acc[ft][tt]);
;     }
;     if (kt + 2 < nk) { WAIT_V(6); } else { WAIT_V(0); }
;     RAW_BARRIER();
;     cur = (cur == 2) ? 0 : cur + 1;
;   }
	ds_read_b128 v[184:187], v153 offset:32768
	ds_read_b128 v[188:191], v153 offset:36864
	ds_read_b128 v[192:195], v146 offset:49152
	ds_read_b128 v[196:199], v146 offset:53248
	s_waitcnt lgkmcnt(4)
	v_mfma_f32_32x32x16_bf16 v[48:63], v[68:71], v[76:79], v[48:63]
	v_mfma_f32_32x32x16_bf16 v[16:31], v[68:71], v[80:83], v[16:31]
	v_lshl_add_u64 v[68:69], v[64:65], 0, s[44:45]
	global_load_lds_dwordx4 v[68:69], off
	v_lshl_add_u64 v[68:69], v[64:65], 0, s[48:49]
	s_mov_b32 m0, s85
	s_nop 0
	global_load_lds_dwordx4 v[68:69], off
	v_lshl_add_u64 v[68:69], v[64:65], 0, s[4:5]
	s_mov_b32 m0, s84
	s_mov_b64 s[4:5], 0x60480
	global_load_lds_dwordx4 v[68:69], off
	v_lshl_add_u64 v[68:69], v[64:65], 0, s[4:5]
	s_mov_b32 m0, s81
	v_mfma_f32_32x32x16_bf16 v[32:47], v[72:75], v[76:79], v[32:47]
	global_load_lds_dwordx4 v[68:69], off
	v_lshl_add_u64 v[68:69], v[66:67], 0, s[44:45]
	s_mov_b32 m0, s80
	s_nop 0
	global_load_lds_dwordx4 v[68:69], off
	v_lshl_add_u64 v[68:69], v[66:67], 0, s[48:49]
	s_mov_b32 m0, s79
	v_mfma_f32_32x32x16_bf16 v[0:15], v[72:75], v[80:83], v[0:15]
	global_load_lds_dwordx4 v[68:69], off
	s_mov_b32 m0, s77
	s_mov_b64 s[4:5], 0x40500
	ds_read_b128 v[68:71], v154 offset:32768
	ds_read_b128 v[72:75], v154 offset:36864
	ds_read_b128 v[76:79], v148 offset:49152
	ds_read_b128 v[80:83], v148 offset:53248
	s_waitcnt lgkmcnt(4)
	v_mfma_f32_32x32x16_bf16 v[48:63], v[184:187], v[192:195], v[48:63]
	v_mfma_f32_32x32x16_bf16 v[16:31], v[184:187], v[196:199], v[16:31]
	v_mfma_f32_32x32x16_bf16 v[32:47], v[188:191], v[192:195], v[32:47]
	v_mfma_f32_32x32x16_bf16 v[0:15], v[188:191], v[196:199], v[0:15]
	ds_read_b128 v[184:187], v155 offset:32768
	ds_read_b128 v[188:191], v155 offset:36864
	ds_read_b128 v[192:195], v150 offset:49152
	ds_read_b128 v[196:199], v150 offset:53248
	s_waitcnt lgkmcnt(4)
	v_mfma_f32_32x32x16_bf16 v[48:63], v[68:71], v[76:79], v[48:63]
	v_mfma_f32_32x32x16_bf16 v[16:31], v[68:71], v[80:83], v[16:31]
	v_mfma_f32_32x32x16_bf16 v[32:47], v[72:75], v[76:79], v[32:47]
	v_mfma_f32_32x32x16_bf16 v[0:15], v[72:75], v[80:83], v[0:15]
	ds_read_b128 v[68:71], v156 offset:32768
	ds_read_b128 v[72:75], v156 offset:36864
	ds_read_b128 v[76:79], v152 offset:49152
	ds_read_b128 v[80:83], v152 offset:53248
	s_waitcnt lgkmcnt(4)
	v_mfma_f32_32x32x16_bf16 v[48:63], v[184:187], v[192:195], v[48:63]
	v_mfma_f32_32x32x16_bf16 v[16:31], v[184:187], v[196:199], v[16:31]
	v_mfma_f32_32x32x16_bf16 v[32:47], v[188:191], v[192:195], v[32:47]
	v_mfma_f32_32x32x16_bf16 v[0:15], v[188:191], v[196:199], v[0:15]
	s_waitcnt vmcnt(6)
	s_waitcnt lgkmcnt(0)
	s_barrier
	ds_read_b128 v[184:187], v157 offset:32768
	ds_read_b128 v[188:191], v157 offset:36864
	ds_read_b128 v[192:195], v158
	ds_read_b128 v[196:199], v158 offset:4096
	s_waitcnt lgkmcnt(4)
	v_mfma_f32_32x32x16_bf16 v[48:63], v[68:71], v[76:79], v[48:63]
	v_mfma_f32_32x32x16_bf16 v[16:31], v[68:71], v[80:83], v[16:31]
	v_lshl_add_u64 v[68:69], v[64:65], 0, s[50:51]
	global_load_lds_dwordx4 v[68:69], off
	v_lshl_add_u64 v[68:69], v[64:65], 0, s[52:53]
	s_mov_b32 m0, s0
	s_nop 0
	global_load_lds_dwordx4 v[68:69], off
	v_lshl_add_u64 v[68:69], v[64:65], 0, s[4:5]
	s_mov_b32 m0, s7
	s_mov_b64 s[4:5], 0x60500
	global_load_lds_dwordx4 v[68:69], off
	v_lshl_add_u64 v[68:69], v[64:65], 0, s[4:5]
	s_mov_b32 m0, s87
	v_mfma_f32_32x32x16_bf16 v[32:47], v[72:75], v[76:79], v[32:47]
	global_load_lds_dwordx4 v[68:69], off
	v_lshl_add_u64 v[68:69], v[66:67], 0, s[50:51]
	s_mov_b32 m0, s86
	s_nop 0
	global_load_lds_dwordx4 v[68:69], off
	v_lshl_add_u64 v[68:69], v[66:67], 0, s[52:53]
	s_mov_b32 m0, s46
	v_mfma_f32_32x32x16_bf16 v[0:15], v[72:75], v[80:83], v[0:15]
	global_load_lds_dwordx4 v[68:69], off
	v_readfirstlane_b32 s84, v117
	s_mov_b32 m0, s84
	v_readfirstlane_b32 s46, v119
	ds_read_b128 v[68:71], v159 offset:32768
	ds_read_b128 v[72:75], v159 offset:36864
	ds_read_b128 v[76:79], v160
	ds_read_b128 v[80:83], v160 offset:4096
	s_waitcnt lgkmcnt(4)
	v_mfma_f32_32x32x16_bf16 v[48:63], v[184:187], v[192:195], v[48:63]
	s_mov_b64 s[4:5], 0x40580
	v_readfirstlane_b32 s47, v121
	v_readfirstlane_b32 s79, v124
	v_readfirstlane_b32 s77, v125
	v_readfirstlane_b32 s80, v126
	v_mfma_f32_32x32x16_bf16 v[16:31], v[184:187], v[196:199], v[16:31]
	v_mfma_f32_32x32x16_bf16 v[32:47], v[188:191], v[192:195], v[32:47]
	v_mfma_f32_32x32x16_bf16 v[0:15], v[188:191], v[196:199], v[0:15]
	ds_read_b128 v[184:187], v161 offset:32768
	ds_read_b128 v[188:191], v161 offset:36864
	ds_read_b128 v[192:195], v163
	ds_read_b128 v[196:199], v163 offset:4096
	s_waitcnt lgkmcnt(4)
	v_mfma_f32_32x32x16_bf16 v[48:63], v[68:71], v[76:79], v[48:63]
	v_mfma_f32_32x32x16_bf16 v[16:31], v[68:71], v[80:83], v[16:31]
	v_mfma_f32_32x32x16_bf16 v[32:47], v[72:75], v[76:79], v[32:47]
	v_mfma_f32_32x32x16_bf16 v[0:15], v[72:75], v[80:83], v[0:15]
	ds_read_b128 v[68:71], v165 offset:32768
	ds_read_b128 v[72:75], v165 offset:36864
	ds_read_b128 v[76:79], v167
	ds_read_b128 v[80:83], v167 offset:4096
	s_waitcnt lgkmcnt(4)
	v_mfma_f32_32x32x16_bf16 v[48:63], v[184:187], v[192:195], v[48:63]
	v_mfma_f32_32x32x16_bf16 v[16:31], v[184:187], v[196:199], v[16:31]
	v_mfma_f32_32x32x16_bf16 v[32:47], v[188:191], v[192:195], v[32:47]
	v_mfma_f32_32x32x16_bf16 v[0:15], v[188:191], v[196:199], v[0:15]
	s_waitcnt vmcnt(6)
	s_waitcnt lgkmcnt(0)
	s_barrier
; #define MFMA(a, b, c) __builtin_amdgcn_mfma_f32_32x32x16_bf16((a), (b), (c), 0, 0, 0)
; #define WAIT_V(n) asm volatile("s_waitcnt vmcnt(%0)" ::"n"(n) : "memory")
; #define RAW_BARRIER() do { asm volatile("s_waitcnt lgkmcnt(0)" ::: "memory"); __builtin_amdgcn_s_barrier(); asm volatile("" ::: "memory"); } while (0)
; #define GLDS_STAGE(slot, kt) do { _Pragma("unroll") for (int i = 0; i < 6; ++i) \
;     __builtin_amdgcn_global_load_lds((const unsigned*)(src[i] + (kt) * 64), (__attribute__((address_space(3))) unsigned*)(smem + (slot) * G_STAGE + (wave + 8 * i) * 1024), 16, 0, 0); } while (0)
; DI void gemm_tile(const u16* __restrict__ X, int ldx, const u16* __restrict__ Wt, int ldw, int K, char* smem,
;                   f32x16 (&acc)[2][2]) {
;     ...
;   for (int kt = 0; kt < nk; ++kt) {
;     const int nxt = (cur >= 1) ? cur - 1 : 2;
;     if (kt + 2 < nk) GLDS_STAGE(nxt, kt + 2);
;     __builtin_amdgcn_sched_barrier(0);
;     const char* st = smem + cur * G_STAGE;
; #pragma unroll
;     for (int ks = 0; ks < 4; ++ks) {
;       bf16x8 a[2], b[2];
; #pragma unroll
;       for (int ft = 0; ft < 2; ++ft) a[ft] = *reinterpret_cast<const bf16x8*>(st + offA[ft] + (((ks * 2 + lh) ^ xa[ft]) << 4));
; #pragma unroll
;       for (int tt = 0; tt < 2; ++tt) b[tt] = *reinterpret_cast<const bf16x8*>(st + offB[tt] + (((ks * 2 + lh) ^ xb[tt]) << 4));
; #pragma unroll
;       for (int ft = 0; ft < 2; ++ft)
; #pragma unroll
;         for (int tt = 0; tt < 2; ++tt) acc[ft][tt] = MFMA(a[ft], b[tt], acc[ft][tt]);
;     }
;     if (kt + 2 < nk) { WAIT_V(6); } else { WAIT_V(0); }
;     RAW_BARRIER();
;     cur = (cur == 2) ? 0 : cur + 1;
;   }
	ds_read_b128 v[184:187], v145 offset:32768
	ds_read_b128 v[188:191], v145 offset:36864
	ds_read_b128 v[192:195], v146
	ds_read_b128 v[196:199], v146 offset:4096
	s_waitcnt lgkmcnt(4)
	v_mfma_f32_32x32x16_bf16 v[48:63], v[68:71], v[76:79], v[48:63]
	v_mfma_f32_32x32x16_bf16 v[16:31], v[68:71], v[80:83], v[16:31]
	v_lshl_add_u64 v[68:69], v[64:65], 0, s[56:57]
	global_load_lds_dwordx4 v[68:69], off
	v_lshl_add_u64 v[68:69], v[64:65], 0, s[58:59]
	s_mov_b32 m0, s46
	s_nop 0
	global_load_lds_dwordx4 v[68:69], off
	v_lshl_add_u64 v[68:69], v[64:65], 0, s[4:5]
	s_mov_b32 m0, s47
	s_mov_b64 s[4:5], 0x60580
	global_load_lds_dwordx4 v[68:69], off
	v_lshl_add_u64 v[68:69], v[64:65], 0, s[4:5]
	s_mov_b32 m0, s79
	v_mfma_f32_32x32x16_bf16 v[32:47], v[72:75], v[76:79], v[32:47]
	global_load_lds_dwordx4 v[68:69], off
	v_lshl_add_u64 v[68:69], v[66:67], 0, s[56:57]
	s_mov_b32 m0, s77
	s_nop 0
	global_load_lds_dwordx4 v[68:69], off
	v_lshl_add_u64 v[68:69], v[66:67], 0, s[58:59]
	s_mov_b32 m0, s80
	v_mfma_f32_32x32x16_bf16 v[0:15], v[72:75], v[80:83], v[0:15]
	global_load_lds_dwordx4 v[68:69], off
	v_readfirstlane_b32 s81, v143
	s_mov_b32 m0, s81
	v_readfirstlane_b32 s0, v131
	ds_read_b128 v[68:71], v147 offset:32768
	ds_read_b128 v[72:75], v147 offset:36864
	ds_read_b128 v[76:79], v148
	ds_read_b128 v[80:83], v148 offset:4096
	s_waitcnt lgkmcnt(4)
	v_mfma_f32_32x32x16_bf16 v[48:63], v[184:187], v[192:195], v[48:63]
	s_mov_b64 s[4:5], 0x40600
	s_mov_b64 s[6:7], 0x60600
	v_mfma_f32_32x32x16_bf16 v[16:31], v[184:187], v[196:199], v[16:31]
	v_mfma_f32_32x32x16_bf16 v[32:47], v[188:191], v[192:195], v[32:47]
	v_mfma_f32_32x32x16_bf16 v[0:15], v[188:191], v[196:199], v[0:15]
	ds_read_b128 v[184:187], v149 offset:32768
	ds_read_b128 v[188:191], v149 offset:36864
	ds_read_b128 v[192:195], v150
	ds_read_b128 v[196:199], v150 offset:4096
	s_waitcnt lgkmcnt(4)
	v_mfma_f32_32x32x16_bf16 v[48:63], v[68:71], v[76:79], v[48:63]
	v_mfma_f32_32x32x16_bf16 v[16:31], v[68:71], v[80:83], v[16:31]
	v_mfma_f32_32x32x16_bf16 v[32:47], v[72:75], v[76:79], v[32:47]
	v_mfma_f32_32x32x16_bf16 v[0:15], v[72:75], v[80:83], v[0:15]
	ds_read_b128 v[68:71], v151 offset:32768
	ds_read_b128 v[72:75], v151 offset:36864
	ds_read_b128 v[76:79], v152
	ds_read_b128 v[80:83], v152 offset:4096
	s_waitcnt lgkmcnt(4)
	v_mfma_f32_32x32x16_bf16 v[48:63], v[184:187], v[192:195], v[48:63]
	v_mfma_f32_32x32x16_bf16 v[16:31], v[184:187], v[196:199], v[16:31]
	v_mfma_f32_32x32x16_bf16 v[32:47], v[188:191], v[192:195], v[32:47]
	v_mfma_f32_32x32x16_bf16 v[0:15], v[188:191], v[196:199], v[0:15]
	s_waitcnt vmcnt(6)
	s_waitcnt lgkmcnt(0)
	s_barrier
	ds_read_b128 v[184:187], v153 offset:32768
	ds_read_b128 v[188:191], v153 offset:36864
	ds_read_b128 v[192:195], v146 offset:49152
	ds_read_b128 v[196:199], v146 offset:53248
	s_waitcnt lgkmcnt(4)
	v_mfma_f32_32x32x16_bf16 v[48:63], v[68:71], v[76:79], v[48:63]
	v_mfma_f32_32x32x16_bf16 v[16:31], v[68:71], v[80:83], v[16:31]
	v_lshl_add_u64 v[68:69], v[64:65], 0, s[60:61]
	global_load_lds_dwordx4 v[68:69], off
	v_lshl_add_u64 v[68:69], v[64:65], 0, s[62:63]
	s_mov_b32 m0, s0
	s_nop 0
	global_load_lds_dwordx4 v[68:69], off
	v_lshl_add_u64 v[68:69], v[64:65], 0, s[4:5]
	v_readfirstlane_b32 s4, v132
	s_mov_b32 m0, s4
	v_readfirstlane_b32 s5, v134
	global_load_lds_dwordx4 v[68:69], off
	v_lshl_add_u64 v[68:69], v[64:65], 0, s[6:7]
	v_readfirstlane_b32 s6, v133
	s_mov_b32 m0, s6
	v_readfirstlane_b32 s7, v135
	global_load_lds_dwordx4 v[68:69], off
	v_lshl_add_u64 v[68:69], v[66:67], 0, s[60:61]
	s_mov_b32 m0, s5
	v_mfma_f32_32x32x16_bf16 v[32:47], v[72:75], v[76:79], v[32:47]
	global_load_lds_dwordx4 v[68:69], off
	v_lshl_add_u64 v[68:69], v[66:67], 0, s[62:63]
	s_mov_b32 m0, s7
	s_nop 0
	global_load_lds_dwordx4 v[68:69], off
	v_mfma_f32_32x32x16_bf16 v[0:15], v[72:75], v[80:83], v[0:15]
	v_readfirstlane_b32 s85, v115
	s_mov_b32 m0, s85
	v_readfirstlane_b32 s85, v136
	ds_read_b128 v[68:71], v154 offset:32768
	ds_read_b128 v[72:75], v154 offset:36864
	ds_read_b128 v[76:79], v148 offset:49152
	ds_read_b128 v[80:83], v148 offset:53248
	s_waitcnt lgkmcnt(4)
	v_mfma_f32_32x32x16_bf16 v[48:63], v[184:187], v[192:195], v[48:63]
	s_mov_b64 s[86:87], 0x40680
	v_mfma_f32_32x32x16_bf16 v[16:31], v[184:187], v[196:199], v[16:31]
	v_mfma_f32_32x32x16_bf16 v[32:47], v[188:191], v[192:195], v[32:47]
	v_mfma_f32_32x32x16_bf16 v[0:15], v[188:191], v[196:199], v[0:15]
	ds_read_b128 v[184:187], v155 offset:32768
	ds_read_b128 v[188:191], v155 offset:36864
	ds_read_b128 v[192:195], v150 offset:49152
	ds_read_b128 v[196:199], v150 offset:53248
	s_waitcnt lgkmcnt(4)
	v_mfma_f32_32x32x16_bf16 v[48:63], v[68:71], v[76:79], v[48:63]
	v_mfma_f32_32x32x16_bf16 v[16:31], v[68:71], v[80:83], v[16:31]
	v_mfma_f32_32x32x16_bf16 v[32:47], v[72:75], v[76:79], v[32:47]
	v_mfma_f32_32x32x16_bf16 v[0:15], v[72:75], v[80:83], v[0:15]
	ds_read_b128 v[68:71], v156 offset:32768
	ds_read_b128 v[72:75], v156 offset:36864
	ds_read_b128 v[76:79], v152 offset:49152
	ds_read_b128 v[80:83], v152 offset:53248
	s_waitcnt lgkmcnt(4)
	v_mfma_f32_32x32x16_bf16 v[48:63], v[184:187], v[192:195], v[48:63]
	v_mfma_f32_32x32x16_bf16 v[16:31], v[184:187], v[196:199], v[16:31]
	v_mfma_f32_32x32x16_bf16 v[32:47], v[188:191], v[192:195], v[32:47]
	v_mfma_f32_32x32x16_bf16 v[0:15], v[188:191], v[196:199], v[0:15]
	s_waitcnt vmcnt(6)
	s_waitcnt lgkmcnt(0)
	s_barrier
; #define MFMA(a, b, c) __builtin_amdgcn_mfma_f32_32x32x16_bf16((a), (b), (c), 0, 0, 0)
; #define WAIT_V(n) asm volatile("s_waitcnt vmcnt(%0)" ::"n"(n) : "memory")
; #define RAW_BARRIER() do { asm volatile("s_waitcnt lgkmcnt(0)" ::: "memory"); __builtin_amdgcn_s_barrier(); asm volatile("" ::: "memory"); } while (0)
; #define GLDS_STAGE(slot, kt) do { _Pragma("unroll") for (int i = 0; i < 6; ++i) \
;     __builtin_amdgcn_global_load_lds((const unsigned*)(src[i] + (kt) * 64), (__attribute__((address_space(3))) unsigned*)(smem + (slot) * G_STAGE + (wave + 8 * i) * 1024), 16, 0, 0); } while (0)
; DI void gemm_tile(const u16* __restrict__ X, int ldx, const u16* __restrict__ Wt, int ldw, int K, char* smem,
;                   f32x16 (&acc)[2][2]) {
;     ...
;   for (int kt = 0; kt < nk; ++kt) {
;     const int nxt = (cur >= 1) ? cur - 1 : 2;
;     if (kt + 2 < nk) GLDS_STAGE(nxt, kt + 2);
;     __builtin_amdgcn_sched_barrier(0);
;     const char* st = smem + cur * G_STAGE;
; #pragma unroll
;     for (int ks = 0; ks < 4; ++ks) {
;       bf16x8 a[2], b[2];
; #pragma unroll
;       for (int ft = 0; ft < 2; ++ft) a[ft] = *reinterpret_cast<const bf16x8*>(st + offA[ft] + (((ks * 2 + lh) ^ xa[ft]) << 4));
; #pragma unroll
;       for (int tt = 0; tt < 2; ++tt) b[tt] = *reinterpret_cast<const bf16x8*>(st + offB[tt] + (((ks * 2 + lh) ^ xb[tt]) << 4));
; #pragma unroll
;       for (int ft = 0; ft < 2; ++ft)
; #pragma unroll
;         for (int tt = 0; tt < 2; ++tt) acc[ft][tt] = MFMA(a[ft], b[tt], acc[ft][tt]);
;     }
;     if (kt + 2 < nk) { WAIT_V(6); } else { WAIT_V(0); }
;     RAW_BARRIER();
;     cur = (cur == 2) ? 0 : cur + 1;
;   }
	ds_read_b128 v[184:187], v157 offset:32768
	ds_read_b128 v[188:191], v157 offset:36864
	ds_read_b128 v[192:195], v158
	ds_read_b128 v[196:199], v158 offset:4096
	s_waitcnt lgkmcnt(4)
	v_mfma_f32_32x32x16_bf16 v[48:63], v[68:71], v[76:79], v[48:63]
	v_mfma_f32_32x32x16_bf16 v[16:31], v[68:71], v[80:83], v[16:31]
	v_lshl_add_u64 v[68:69], v[64:65], 0, s[64:65]
	global_load_lds_dwordx4 v[68:69], off
	v_lshl_add_u64 v[68:69], v[64:65], 0, s[66:67]
	s_mov_b32 m0, s85
	v_readfirstlane_b32 s85, v127
	global_load_lds_dwordx4 v[68:69], off
	v_lshl_add_u64 v[68:69], v[64:65], 0, s[86:87]
	s_mov_b32 m0, s85
	s_mov_b64 s[86:87], 0x60680
	v_readfirstlane_b32 s85, v128
	global_load_lds_dwordx4 v[68:69], off
	v_lshl_add_u64 v[68:69], v[64:65], 0, s[86:87]
	s_mov_b32 m0, s85
	v_readfirstlane_b32 s85, v129
	global_load_lds_dwordx4 v[68:69], off
	v_lshl_add_u64 v[68:69], v[66:67], 0, s[64:65]
	s_mov_b32 m0, s85
	v_readfirstlane_b32 s85, v130
	global_load_lds_dwordx4 v[68:69], off
	v_lshl_add_u64 v[68:69], v[66:67], 0, s[66:67]
	s_mov_b32 m0, s85
	v_mfma_f32_32x32x16_bf16 v[32:47], v[72:75], v[76:79], v[32:47]
	global_load_lds_dwordx4 v[68:69], off
	v_mfma_f32_32x32x16_bf16 v[0:15], v[72:75], v[80:83], v[0:15]
	s_mov_b32 m0, s84
	s_mov_b64 s[84:85], 0x40700
	ds_read_b128 v[68:71], v159 offset:32768
	ds_read_b128 v[72:75], v159 offset:36864
	ds_read_b128 v[76:79], v160
	ds_read_b128 v[80:83], v160 offset:4096
	s_waitcnt lgkmcnt(4)
	v_mfma_f32_32x32x16_bf16 v[48:63], v[184:187], v[192:195], v[48:63]
	v_mfma_f32_32x32x16_bf16 v[16:31], v[184:187], v[196:199], v[16:31]
	v_mfma_f32_32x32x16_bf16 v[32:47], v[188:191], v[192:195], v[32:47]
	v_mfma_f32_32x32x16_bf16 v[0:15], v[188:191], v[196:199], v[0:15]
	ds_read_b128 v[184:187], v161 offset:32768
	ds_read_b128 v[188:191], v161 offset:36864
	ds_read_b128 v[192:195], v163
	ds_read_b128 v[196:199], v163 offset:4096
	s_waitcnt lgkmcnt(4)
	v_mfma_f32_32x32x16_bf16 v[48:63], v[68:71], v[76:79], v[48:63]
	v_mfma_f32_32x32x16_bf16 v[16:31], v[68:71], v[80:83], v[16:31]
	v_mfma_f32_32x32x16_bf16 v[32:47], v[72:75], v[76:79], v[32:47]
	v_mfma_f32_32x32x16_bf16 v[0:15], v[72:75], v[80:83], v[0:15]
	ds_read_b128 v[68:71], v165 offset:32768
	ds_read_b128 v[72:75], v165 offset:36864
	ds_read_b128 v[76:79], v167
	ds_read_b128 v[80:83], v167 offset:4096
	s_waitcnt lgkmcnt(4)
	v_mfma_f32_32x32x16_bf16 v[48:63], v[184:187], v[192:195], v[48:63]
	v_mfma_f32_32x32x16_bf16 v[16:31], v[184:187], v[196:199], v[16:31]
	v_mfma_f32_32x32x16_bf16 v[32:47], v[188:191], v[192:195], v[32:47]
	v_mfma_f32_32x32x16_bf16 v[0:15], v[188:191], v[196:199], v[0:15]
	s_waitcnt vmcnt(6)
	s_waitcnt lgkmcnt(0)
	s_barrier
	ds_read_b128 v[184:187], v145 offset:32768
	ds_read_b128 v[188:191], v145 offset:36864
	ds_read_b128 v[192:195], v146
	ds_read_b128 v[196:199], v146 offset:4096
	s_waitcnt lgkmcnt(4)
	v_mfma_f32_32x32x16_bf16 v[48:63], v[68:71], v[76:79], v[48:63]
	v_mfma_f32_32x32x16_bf16 v[16:31], v[68:71], v[80:83], v[16:31]
	v_lshl_add_u64 v[68:69], v[64:65], 0, s[68:69]
	global_load_lds_dwordx4 v[68:69], off
	v_lshl_add_u64 v[68:69], v[64:65], 0, s[70:71]
	s_mov_b32 m0, s46
	s_nop 0
	global_load_lds_dwordx4 v[68:69], off
	v_lshl_add_u64 v[68:69], v[64:65], 0, s[84:85]
	s_mov_b32 m0, s47
	s_mov_b64 s[46:47], 0x60700
	global_load_lds_dwordx4 v[68:69], off
	v_lshl_add_u64 v[68:69], v[64:65], 0, s[46:47]
	s_mov_b32 m0, s79
	v_mfma_f32_32x32x16_bf16 v[32:47], v[72:75], v[76:79], v[32:47]
	global_load_lds_dwordx4 v[68:69], off
	v_lshl_add_u64 v[68:69], v[66:67], 0, s[68:69]
	s_mov_b32 m0, s77
	s_nop 0
	global_load_lds_dwordx4 v[68:69], off
	v_lshl_add_u64 v[68:69], v[66:67], 0, s[70:71]
	s_mov_b32 m0, s80
	v_mfma_f32_32x32x16_bf16 v[0:15], v[72:75], v[80:83], v[0:15]
	global_load_lds_dwordx4 v[68:69], off
	s_mov_b32 m0, s81
	s_mov_b64 s[46:47], 0x40780
	ds_read_b128 v[68:71], v147 offset:32768
	ds_read_b128 v[72:75], v147 offset:36864
	ds_read_b128 v[76:79], v148
	ds_read_b128 v[80:83], v148 offset:4096
	s_waitcnt lgkmcnt(4)
	v_mfma_f32_32x32x16_bf16 v[48:63], v[184:187], v[192:195], v[48:63]
	v_mfma_f32_32x32x16_bf16 v[16:31], v[184:187], v[196:199], v[16:31]
	v_mfma_f32_32x32x16_bf16 v[32:47], v[188:191], v[192:195], v[32:47]
	v_mfma_f32_32x32x16_bf16 v[0:15], v[188:191], v[196:199], v[0:15]
	ds_read_b128 v[184:187], v149 offset:32768
	ds_read_b128 v[188:191], v149 offset:36864
	ds_read_b128 v[192:195], v150
	ds_read_b128 v[196:199], v150 offset:4096
	s_waitcnt lgkmcnt(4)
	v_mfma_f32_32x32x16_bf16 v[48:63], v[68:71], v[76:79], v[48:63]
	v_mfma_f32_32x32x16_bf16 v[16:31], v[68:71], v[80:83], v[16:31]
	v_mfma_f32_32x32x16_bf16 v[32:47], v[72:75], v[76:79], v[32:47]
	v_mfma_f32_32x32x16_bf16 v[0:15], v[72:75], v[80:83], v[0:15]
	ds_read_b128 v[68:71], v151 offset:32768
	ds_read_b128 v[72:75], v151 offset:36864
	ds_read_b128 v[76:79], v152
	ds_read_b128 v[80:83], v152 offset:4096
	s_waitcnt lgkmcnt(4)
	v_mfma_f32_32x32x16_bf16 v[48:63], v[184:187], v[192:195], v[48:63]
	v_mfma_f32_32x32x16_bf16 v[16:31], v[184:187], v[196:199], v[16:31]
	v_mfma_f32_32x32x16_bf16 v[32:47], v[188:191], v[192:195], v[32:47]
	v_mfma_f32_32x32x16_bf16 v[0:15], v[188:191], v[196:199], v[0:15]
	s_waitcnt vmcnt(6)
	s_waitcnt lgkmcnt(0)
	s_barrier
; #define MFMA(a, b, c) __builtin_amdgcn_mfma_f32_32x32x16_bf16((a), (b), (c), 0, 0, 0)
; #define WAIT_V(n) asm volatile("s_waitcnt vmcnt(%0)" ::"n"(n) : "memory")
; #define RAW_BARRIER() do { asm volatile("s_waitcnt lgkmcnt(0)" ::: "memory"); __builtin_amdgcn_s_barrier(); asm volatile("" ::: "memory"); } while (0)
; #define GLDS_STAGE(slot, kt) do { _Pragma("unroll") for (int i = 0; i < 6; ++i) \
;     __builtin_amdgcn_global_load_lds((const unsigned*)(src[i] + (kt) * 64), (__attribute__((address_space(3))) unsigned*)(smem + (slot) * G_STAGE + (wave + 8 * i) * 1024), 16, 0, 0); } while (0)
; DI void gemm_tile(const u16* __restrict__ X, int ldx, const u16* __restrict__ Wt, int ldw, int K, char* smem,
;                   f32x16 (&acc)[2][2]) {
;     ...
;   for (int kt = 0; kt < nk; ++kt) {
;     const int nxt = (cur >= 1) ? cur - 1 : 2;
;     if (kt + 2 < nk) GLDS_STAGE(nxt, kt + 2);
;     __builtin_amdgcn_sched_barrier(0);
;     const char* st = smem + cur * G_STAGE;
; #pragma unroll
;     for (int ks = 0; ks < 4; ++ks) {
;       bf16x8 a[2], b[2];
; #pragma unroll
;       for (int ft = 0; ft < 2; ++ft) a[ft] = *reinterpret_cast<const bf16x8*>(st + offA[ft] + (((ks * 2 + lh) ^ xa[ft]) << 4));
; #pragma unroll
;       for (int tt = 0; tt < 2; ++tt) b[tt] = *reinterpret_cast<const bf16x8*>(st + offB[tt] + (((ks * 2 + lh) ^ xb[tt]) << 4));
; #pragma unroll
;       for (int ft = 0; ft < 2; ++ft)
; #pragma unroll
;         for (int tt = 0; tt < 2; ++tt) acc[ft][tt] = MFMA(a[ft], b[tt], acc[ft][tt]);
;     }
;     if (kt + 2 < nk) { WAIT_V(6); } else { WAIT_V(0); }
;     RAW_BARRIER();
;     cur = (cur == 2) ? 0 : cur + 1;
;   }
	ds_read_b128 v[184:187], v153 offset:32768
	ds_read_b128 v[192:195], v146 offset:49152
	ds_read_b128 v[196:199], v146 offset:53248
	ds_read_b128 v[188:191], v153 offset:36864
	s_waitcnt lgkmcnt(4)
	v_mfma_f32_32x32x16_bf16 v[48:63], v[68:71], v[76:79], v[48:63]
	v_mfma_f32_32x32x16_bf16 v[16:31], v[68:71], v[80:83], v[16:31]
	v_lshl_add_u64 v[68:69], v[64:65], 0, s[72:73]
	global_load_lds_dwordx4 v[68:69], off
	v_lshl_add_u64 v[68:69], v[64:65], 0, s[74:75]
	s_mov_b32 m0, s0
	s_nop 0
	global_load_lds_dwordx4 v[68:69], off
	v_lshl_add_u64 v[68:69], v[64:65], 0, s[46:47]
	s_mov_b32 m0, s4
	s_mov_b64 s[46:47], 0x60780
	global_load_lds_dwordx4 v[68:69], off
	v_lshl_add_u64 v[64:65], v[64:65], 0, s[46:47]
	s_mov_b32 m0, s6
	v_mfma_f32_32x32x16_bf16 v[32:47], v[72:75], v[76:79], v[32:47]
	global_load_lds_dwordx4 v[64:65], off
	v_lshl_add_u64 v[64:65], v[66:67], 0, s[72:73]
	s_mov_b32 m0, s5
	s_nop 0
	global_load_lds_dwordx4 v[64:65], off
	v_lshl_add_u64 v[64:65], v[66:67], 0, s[74:75]
	s_mov_b32 m0, s7
	v_mfma_f32_32x32x16_bf16 v[0:15], v[72:75], v[80:83], v[0:15]
	global_load_lds_dwordx4 v[64:65], off
	ds_read_b128 v[64:67], v154 offset:32768
	ds_read_b128 v[68:71], v148 offset:49152
	ds_read_b128 v[72:75], v148 offset:53248
	ds_read_b128 v[76:79], v154 offset:36864
	s_waitcnt lgkmcnt(4)
	v_mfma_f32_32x32x16_bf16 v[48:63], v[184:187], v[192:195], v[48:63]
	v_mfma_f32_32x32x16_bf16 v[16:31], v[184:187], v[196:199], v[16:31]
	v_mfma_f32_32x32x16_bf16 v[32:47], v[188:191], v[192:195], v[32:47]
	v_mfma_f32_32x32x16_bf16 v[0:15], v[188:191], v[196:199], v[0:15]
	ds_read_b128 v[184:187], v155 offset:32768
	ds_read_b128 v[192:195], v150 offset:49152
	ds_read_b128 v[196:199], v150 offset:53248
	ds_read_b128 v[188:191], v155 offset:36864
	s_waitcnt lgkmcnt(4)
	v_mfma_f32_32x32x16_bf16 v[48:63], v[64:67], v[68:71], v[48:63]
	v_mfma_f32_32x32x16_bf16 v[16:31], v[64:67], v[72:75], v[16:31]
	v_mfma_f32_32x32x16_bf16 v[32:47], v[76:79], v[68:71], v[32:47]
	v_mfma_f32_32x32x16_bf16 v[0:15], v[76:79], v[72:75], v[0:15]
	ds_read_b128 v[64:67], v156 offset:32768
	ds_read_b128 v[68:71], v152 offset:49152
	ds_read_b128 v[72:75], v152 offset:53248
	ds_read_b128 v[76:79], v156 offset:36864
	s_waitcnt lgkmcnt(4)
	v_mfma_f32_32x32x16_bf16 v[48:63], v[184:187], v[192:195], v[48:63]
	v_mfma_f32_32x32x16_bf16 v[16:31], v[184:187], v[196:199], v[16:31]
	v_mfma_f32_32x32x16_bf16 v[32:47], v[188:191], v[192:195], v[32:47]
	v_mfma_f32_32x32x16_bf16 v[0:15], v[188:191], v[196:199], v[0:15]
	s_waitcnt vmcnt(6)
	s_waitcnt lgkmcnt(0)
	s_barrier
	ds_read_b128 v[184:187], v157 offset:32768
	ds_read_b128 v[192:195], v158
	ds_read_b128 v[196:199], v158 offset:4096
	ds_read_b128 v[188:191], v157 offset:36864
	s_waitcnt lgkmcnt(4)
	v_mfma_f32_32x32x16_bf16 v[48:63], v[64:67], v[68:71], v[48:63]
	v_mfma_f32_32x32x16_bf16 v[16:31], v[64:67], v[72:75], v[16:31]
	v_mfma_f32_32x32x16_bf16 v[32:47], v[76:79], v[68:71], v[32:47]
	v_mfma_f32_32x32x16_bf16 v[0:15], v[76:79], v[72:75], v[0:15]
	ds_read_b128 v[64:67], v159 offset:32768
	ds_read_b128 v[68:71], v160
	ds_read_b128 v[72:75], v160 offset:4096
	ds_read_b128 v[76:79], v159 offset:36864
	s_waitcnt lgkmcnt(4)
	v_mfma_f32_32x32x16_bf16 v[48:63], v[184:187], v[192:195], v[48:63]
	v_mfma_f32_32x32x16_bf16 v[16:31], v[184:187], v[196:199], v[16:31]
	v_mfma_f32_32x32x16_bf16 v[32:47], v[188:191], v[192:195], v[32:47]
	v_mfma_f32_32x32x16_bf16 v[0:15], v[188:191], v[196:199], v[0:15]
	ds_read_b128 v[184:187], v161 offset:32768
	ds_read_b128 v[192:195], v163
	ds_read_b128 v[196:199], v163 offset:4096
	ds_read_b128 v[188:191], v161 offset:36864
	s_waitcnt lgkmcnt(4)
	v_mfma_f32_32x32x16_bf16 v[48:63], v[64:67], v[68:71], v[48:63]
	v_mfma_f32_32x32x16_bf16 v[16:31], v[64:67], v[72:75], v[16:31]
	v_mfma_f32_32x32x16_bf16 v[32:47], v[76:79], v[68:71], v[32:47]
	v_mfma_f32_32x32x16_bf16 v[0:15], v[76:79], v[72:75], v[0:15]
	s_waitcnt lgkmcnt(0)
	v_mfma_f32_32x32x16_bf16 v[48:63], v[184:187], v[192:195], v[48:63]
	v_mfma_f32_32x32x16_bf16 v[16:31], v[184:187], v[196:199], v[16:31]
	v_mfma_f32_32x32x16_bf16 v[32:47], v[188:191], v[192:195], v[32:47]
	v_mfma_f32_32x32x16_bf16 v[0:15], v[188:191], v[196:199], v[0:15]
	ds_read_b128 v[64:67], v165 offset:32768
	ds_read_b128 v[68:71], v167
	ds_read_b128 v[72:75], v167 offset:4096
	ds_read_b128 v[76:79], v165 offset:36864
	s_waitcnt vmcnt(0)
	s_waitcnt lgkmcnt(0)
	s_barrier
; template <int MODE>
; DI void phase_gemm(const Params& p, const u16* X, const u16* Wt, int N, const float* resid, float* outf, u16* outb, int ldo, char* smem) {
;     ...
; #pragma unroll
;       for (int tt = 0; tt < 2; ++tt) {
;         const int tok = mt * 256 + tq * 64 + tt * 32 + lr;
; #pragma unroll
;         for (int ft = 0; ft < 2; ++ft)
; #pragma unroll
;           for (int g = 0; g < 4; ++g) {
;             const int f = nt * 128 + fw * 64 + ft * 32 + 8 * g + 4 * lh;
;             if (MODE == 2) {
;               const int hh = f >> 8, fh = f & 255, ks = fh >> 4, lane2 = ((fh >> 3) & 1) * 32 + lr;
;               st4bf(outb + ((((size_t)(tok >> 5) * 4 + hh) * 16 + ks) * 64 + lane2) * 8 + 4 * lh, acc[ft][tt][4 * g], acc[ft][tt][4 * g + 1], acc[ft][tt][4 * g + 2], acc[ft][tt][4 * g + 3]);
;             } else {
;               const int hh = f >> 8, fq = f & 127, half = (f >> 7) & 1, ks = fq >> 4, lane2 = ((fq >> 3) & 1) * 32 + lr;
;               st4bf(outb + (((((size_t)(tok >> 5) * 8 + hh) * 2 + half) * 8 + ks) * 64 + lane2) * 8 + 4 * lh, acc[ft][tt][4 * g], acc[ft][tt][4 * g + 1], acc[ft][tt][4 * g + 2], acc[ft][tt][4 * g + 3]);
;             }
;           }
;       }
	s_waitcnt lgkmcnt(0)
	v_mfma_f32_32x32x16_bf16 v[48:63], v[64:67], v[68:71], v[48:63]
	v_mfma_f32_32x32x16_bf16 v[16:31], v[64:67], v[72:75], v[16:31]
	v_mfma_f32_32x32x16_bf16 v[32:47], v[76:79], v[68:71], v[32:47]
	v_mfma_f32_32x32x16_bf16 v[0:15], v[76:79], v[72:75], v[0:15]
	ds_read_b128 v[64:67], v145 offset:32768
	ds_read_b128 v[68:71], v146
	ds_read_b128 v[72:75], v145 offset:36864
	ds_read_b128 v[76:79], v146 offset:4096
	v_lshl_add_u32 v104, s76, 8, v111
	s_add_i32 s54, s54, s55
	s_waitcnt lgkmcnt(0)
	v_mfma_f32_32x32x16_bf16 v[48:63], v[64:67], v[68:71], v[48:63]
	v_mfma_f32_32x32x16_bf16 v[16:31], v[64:67], v[76:79], v[16:31]
	v_mfma_f32_32x32x16_bf16 v[32:47], v[72:75], v[68:71], v[32:47]
	ds_read_b128 v[64:67], v147 offset:32768
	ds_read_b128 v[68:71], v148
	ds_read_b128 v[96:99], v147 offset:36864
	ds_read_b128 v[100:103], v148 offset:4096
	v_mfma_f32_32x32x16_bf16 v[0:15], v[72:75], v[76:79], v[0:15]
	ds_read_b128 v[92:95], v149 offset:32768
	ds_read_b128 v[72:75], v149 offset:36864
	ds_read_b128 v[88:91], v150
	ds_read_b128 v[80:83], v150 offset:4096
	s_waitcnt lgkmcnt(0)
	v_mfma_f32_32x32x16_bf16 v[48:63], v[64:67], v[68:71], v[48:63]
	v_mfma_f32_32x32x16_bf16 v[16:31], v[64:67], v[100:103], v[16:31]
	v_mfma_f32_32x32x16_bf16 v[32:47], v[96:99], v[68:71], v[32:47]
	ds_read_b128 v[84:87], v151 offset:32768
	ds_read_b128 v[64:67], v151 offset:36864
	ds_read_b128 v[76:79], v152
	ds_read_b128 v[68:71], v152 offset:4096
	s_waitcnt vmcnt(0)
	s_waitcnt lgkmcnt(0)
	s_barrier
	v_mfma_f32_32x32x16_bf16 v[0:15], v[96:99], v[100:103], v[0:15]
	v_lshrrev_b32_e32 v96, 1, v104
	v_and_or_b32 v169, s98, 15, v96
	v_lshlrev_b32_e32 v96, 9, v169
	v_or_b32_e32 v98, v110, v96
	v_or_b32_e32 v104, v98, v168
	v_or_b32_e32 v99, v118, v96
	v_or_b32_e32 v100, v114, v96
	v_mfma_f32_32x32x16_bf16 v[48:63], v[92:95], v[88:91], v[48:63]
	v_or_b32_e32 v102, v120, v96
	v_lshl_add_u64 v[96:97], v[104:105], 4, v[112:113]
	v_or_b32_e32 v104, v98, v116
	s_add_i32 s3, s3, s94
	s_cmpk_lt_u32 s3, 0x100
	v_mfma_f32_32x32x16_bf16 v[16:31], v[92:95], v[80:83], v[16:31]
	v_lshl_add_u64 v[92:93], v[104:105], 4, v[112:113]
	v_or_b32_e32 v104, v99, v168
	v_lshl_add_u64 v[94:95], v[104:105], 4, v[112:113]
	v_or_b32_e32 v104, v99, v116
	v_lshl_add_u64 v[98:99], v[104:105], 4, v[112:113]
	v_or_b32_e32 v104, v100, v168
	v_mfma_f32_32x32x16_bf16 v[32:47], v[72:75], v[88:91], v[32:47]
	v_lshl_add_u64 v[88:89], v[104:105], 4, v[112:113]
	v_or_b32_e32 v104, v100, v116
	v_lshl_add_u64 v[90:91], v[104:105], 4, v[112:113]
	v_or_b32_e32 v104, v102, v168
	v_lshl_add_u64 v[100:101], v[104:105], 4, v[112:113]
	v_or_b32_e32 v104, v102, v116
	v_lshl_add_u64 v[102:103], v[104:105], 4, v[112:113]
	v_mfma_f32_32x32x16_bf16 v[0:15], v[72:75], v[80:83], v[0:15]
	v_or_b32_e32 v104, 16, v169
	v_lshlrev_b64 v[72:73], 9, v[104:105]
	v_or_b32_e32 v171, v72, v120
	v_or_b32_e32 v80, v72, v110
	v_or_b32_e32 v104, v72, v118
	v_or_b32_e32 v169, v72, v114
	v_or_b32_e32 v72, v171, v168
	s_waitcnt lgkmcnt(0)
	v_mfma_f32_32x32x16_bf16 v[48:63], v[84:87], v[76:79], v[48:63]
	v_mov_b32_e32 v75, v73
	v_mov_b32_e32 v81, v73
	v_mov_b32_e32 v83, v73
	v_mov_b32_e32 v173, v73
	v_mov_b32_e32 v175, v73
	v_mov_b32_e32 v181, v73
	v_or_b32_e32 v74, v80, v168
	v_mfma_f32_32x32x16_bf16 v[16:31], v[84:87], v[68:71], v[16:31]
	v_or_b32_e32 v80, v80, v116
	v_or_b32_e32 v82, v104, v168
	v_or_b32_e32 v172, v104, v116
	v_or_b32_e32 v174, v169, v168
	v_or_b32_e32 v180, v169, v116
	v_lshl_add_u64 v[86:87], v[72:73], 4, v[112:113]
	v_or_b32_e32 v72, v171, v116
	v_mfma_f32_32x32x16_bf16 v[32:47], v[64:67], v[76:79], v[32:47]
	v_cvt_pk_bf16_f32 v48, v48, v49
	v_cvt_pk_bf16_f32 v49, v50, v51
	v_lshl_add_u64 v[74:75], v[74:75], 4, v[112:113]
	v_lshl_add_u64 v[80:81], v[80:81], 4, v[112:113]
	v_lshl_add_u64 v[76:77], v[82:83], 4, v[112:113]
	v_lshl_add_u64 v[78:79], v[172:173], 4, v[112:113]
	v_lshl_add_u64 v[82:83], v[174:175], 4, v[112:113]
	v_mfma_f32_32x32x16_bf16 v[0:15], v[64:67], v[68:71], v[0:15]
	v_lshl_add_u64 v[84:85], v[180:181], 4, v[112:113]
	v_lshl_add_u64 v[72:73], v[72:73], 4, v[112:113]
	v_cvt_pk_bf16_f32 v50, v52, v53
	v_cvt_pk_bf16_f32 v51, v54, v55
	v_cvt_pk_bf16_f32 v52, v56, v57
	v_cvt_pk_bf16_f32 v53, v58, v59
	v_cvt_pk_bf16_f32 v54, v60, v61
	v_cvt_pk_bf16_f32 v55, v62, v63
	v_cvt_pk_bf16_f32 v32, v32, v33
	v_cvt_pk_bf16_f32 v33, v34, v35
	v_cvt_pk_bf16_f32 v34, v36, v37
	v_cvt_pk_bf16_f32 v35, v38, v39
	v_cvt_pk_bf16_f32 v36, v40, v41
	v_cvt_pk_bf16_f32 v37, v42, v43
	v_cvt_pk_bf16_f32 v38, v44, v45
	v_cvt_pk_bf16_f32 v39, v46, v47
	v_cvt_pk_bf16_f32 v16, v16, v17
	v_cvt_pk_bf16_f32 v17, v18, v19
	v_cvt_pk_bf16_f32 v18, v20, v21
	v_cvt_pk_bf16_f32 v19, v22, v23
	v_cvt_pk_bf16_f32 v20, v24, v25
	v_cvt_pk_bf16_f32 v21, v26, v27
	v_cvt_pk_bf16_f32 v22, v28, v29
	v_cvt_pk_bf16_f32 v23, v30, v31
	v_cvt_pk_bf16_f32 v0, v0, v1
	v_cvt_pk_bf16_f32 v1, v2, v3
	v_cvt_pk_bf16_f32 v2, v4, v5
	v_cvt_pk_bf16_f32 v3, v6, v7
	v_cvt_pk_bf16_f32 v4, v8, v9
	v_cvt_pk_bf16_f32 v5, v10, v11
	v_cvt_pk_bf16_f32 v6, v12, v13
	v_cvt_pk_bf16_f32 v7, v14, v15
	global_store_dwordx2 v[96:97], v[48:49], off
	global_store_dwordx2 v[92:93], v[50:51], off
	global_store_dwordx2 v[94:95], v[52:53], off
	global_store_dwordx2 v[98:99], v[54:55], off
	global_store_dwordx2 v[88:89], v[32:33], off
	global_store_dwordx2 v[90:91], v[34:35], off
	global_store_dwordx2 v[100:101], v[36:37], off
	global_store_dwordx2 v[102:103], v[38:39], off
	global_store_dwordx2 v[74:75], v[16:17], off
	global_store_dwordx2 v[80:81], v[18:19], off
	global_store_dwordx2 v[76:77], v[20:21], off
	global_store_dwordx2 v[78:79], v[22:23], off
	global_store_dwordx2 v[82:83], v[0:1], off
	global_store_dwordx2 v[84:85], v[2:3], off
	global_store_dwordx2 v[86:87], v[4:5], off
	global_store_dwordx2 v[72:73], v[6:7], off
	s_cbranch_scc1 .LBB0_906
	v_readlane_b32 s60, v255, 43
	v_readlane_b32 s61, v255, 44

; __global__ void __launch_bounds__(512) fwd_megakernel(Params p) {
;   __shared__ __attribute__((aligned(1024))) char smem[155648];
	.amdhsa_kernel _Z14fwd_megakernel6Params
		.amdhsa_group_segment_fixed_size 155648
		.amdhsa_private_segment_fixed_size 0
		.amdhsa_kernarg_size 456
		.amdhsa_user_sgpr_count 2
		.amdhsa_user_sgpr_dispatch_ptr 0
		.amdhsa_user_sgpr_queue_ptr 0
		.amdhsa_user_sgpr_kernarg_segment_ptr 1
		.amdhsa_user_sgpr_dispatch_id 0
		.amdhsa_user_sgpr_kernarg_preload_length 0
		.amdhsa_user_sgpr_kernarg_preload_offset 0
		.amdhsa_user_sgpr_private_segment_size 0
		.amdhsa_uses_dynamic_stack 0
		.amdhsa_enable_private_segment 0
		.amdhsa_system_sgpr_workgroup_id_x 1
		.amdhsa_system_sgpr_workgroup_id_y 0
		.amdhsa_system_sgpr_workgroup_id_z 0
		.amdhsa_system_sgpr_workgroup_info 0
		.amdhsa_system_vgpr_workitem_id 2
		.amdhsa_next_free_vgpr 256
		.amdhsa_next_free_sgpr 100
		.amdhsa_accum_offset 256
		.amdhsa_reserve_vcc 1
		.amdhsa_float_round_mode_32 0
		.amdhsa_float_round_mode_16_64 0
		.amdhsa_float_denorm_mode_32 3
		.amdhsa_float_denorm_mode_16_64 3
		.amdhsa_dx10_clamp 1
		.amdhsa_ieee_mode 1
		.amdhsa_fp16_overflow 0
		.amdhsa_tg_split 0
		.amdhsa_exception_fp_ieee_invalid_op 0
		.amdhsa_exception_fp_denorm_src 0
		.amdhsa_exception_fp_ieee_div_zero 0
		.amdhsa_exception_fp_ieee_overflow 0
		.amdhsa_exception_fp_ieee_underflow 0
		.amdhsa_exception_fp_ieee_inexact 0
		.amdhsa_exception_int_div_zero 0
	.end_amdhsa_kernel

; __global__ void __launch_bounds__(512) fwd_megakernel(Params p) {
;   __shared__ __attribute__((aligned(1024))) char smem[155648];
amdhsa.kernels:
  - .agpr_count:     0
    .args:
      - .offset:         0
        .size:           200
        .value_kind:     by_value
      - .offset:         200
        .size:           4
        .value_kind:     hidden_block_count_x
      - .offset:         204
        .size:           4
        .value_kind:     hidden_block_count_y
      - .offset:         208
        .size:           4
        .value_kind:     hidden_block_count_z
      - .offset:         212
        .size:           2
        .value_kind:     hidden_group_size_x
      - .offset:         214
        .size:           2
        .value_kind:     hidden_group_size_y
      - .offset:         216
        .size:           2
        .value_kind:     hidden_group_size_z
      - .offset:         218
        .size:           2
        .value_kind:     hidden_remainder_x
      - .offset:         220
        .size:           2
        .value_kind:     hidden_remainder_y
      - .offset:         222
        .size:           2
        .value_kind:     hidden_remainder_z
      - .offset:         240
        .size:           8
        .value_kind:     hidden_global_offset_x
      - .offset:         248
        .size:           8
        .value_kind:     hidden_global_offset_y
      - .offset:         256
        .size:           8
        .value_kind:     hidden_global_offset_z
      - .offset:         264
        .size:           2
        .value_kind:     hidden_grid_dims
      - .offset:         288
        .size:           8
        .value_kind:     hidden_multigrid_sync_arg
    .group_segment_fixed_size: 155648
    .kernarg_segment_align: 8
    .kernarg_segment_size: 456
    .language:       OpenCL C
    .language_version:
      - 2
      - 0
    .max_flat_workgroup_size: 512
    .name:           _Z14fwd_megakernel6Params
    .private_segment_fixed_size: 0
    .sgpr_count:     106
    .sgpr_spill_count: 58
    .symbol:         _Z14fwd_megakernel6Params.kd
    .uniform_work_group_size: 1
    .uses_dynamic_stack: false
    .vgpr_count:     256
    .vgpr_spill_count: 0
    .wavefront_size: 64
